# GLU phase tail round split into quarter units as well
# speedup vs baseline: 1.0224x; 1.0015x over previous
.LBB0_1390:
	v_readlane_b32 s2, v253, 0
	v_readlane_b32 s3, v253, 1
	s_cmp_lt_i32 s2, 6
	s_cselect_b64 s[2:3], -1, 0
	s_and_b64 s[0:1], s[2:3], s[0:1]
	s_andn2_b64 vcc, exec, s[0:1]
	s_cbranch_vccnz .LBB0_1411
	s_mov_b64 s[0:1], s[92:93]
	v_mov_b32_e32 v8, v180
	s_cmpk_gt_i32 s94, 0x201
	s_nop 0
	v_readfirstlane_b32 s17, v8
	s_cbranch_scc1 .LBB0_1411
	v_lshlrev_b32_e32 v0, 4, v8
	v_add_u32_e32 v1, 0x2000, v0
	v_ashrrev_i32_e32 v2, 31, v1
	v_lshrrev_b32_e32 v2, 22, v2
	v_add_u32_e32 v2, v1, v2
	v_ashrrev_i32_e32 v9, 10, v2
	v_mul_i32_i24_e32 v2, 0x400, v9
	v_sub_u32_e32 v1, v1, v2
	v_lshrrev_b32_e32 v2, 4, v1
	v_bitop3_b32 v1, v2, v1, 32 bitop3:0x6c
	v_ashrrev_i32_e32 v2, 31, v1
	v_lshrrev_b32_e32 v2, 26, v2
	v_add_u32_e32 v2, v1, v2
	v_lshlrev_b32_e32 v3, 3, v9
	v_ashrrev_i32_e32 v10, 6, v2
	v_and_b32_e32 v3, -16, v3
	v_add_u32_e32 v3, v10, v3
	v_and_b32_e32 v4, 3, v10
	s_mov_b32 s10, 0x3fffe0
	v_lshrrev_b32_e32 v5, 2, v3
	v_lshlrev_b32_e32 v6, 1, v3
	v_and_b32_e32 v2, 0xc0, v2
	v_and_or_b32 v4, v3, s10, v4
	v_and_b32_e32 v5, 4, v5
	v_and_b32_e32 v6, 24, v6
	v_sub_u32_e32 v1, v1, v2
	v_mov_b32_e32 v2, 1
	v_or3_b32 v4, v4, v5, v6
	v_lshlrev_b32_e32 v5, 5, v9
	v_ashrrev_i16_sdwa v1, v2, sext(v1) dst_sel:DWORD dst_unused:UNUSED_PAD src0_sel:DWORD src1_sel:BYTE_0
	v_and_b32_e32 v5, 32, v5
	v_bfe_i32 v11, v1, 0, 16
	v_add_lshl_u32 v1, v5, v11, 1
	s_waitcnt vmcnt(0)
	v_lshl_add_u32 v144, v4, 10, v1
	v_lshl_add_u32 v146, v3, 10, v1
	v_bfe_i32 v1, v8, 27, 1
	v_lshrrev_b32_e32 v1, 22, v1
	v_add_u32_e32 v1, v0, v1
	v_and_b32_e32 v1, 0xfffffc00, v1
	s_load_dwordx2 s[4:5], s[0:1], 0x120
	s_load_dwordx2 s[6:7], s[0:1], 0xa8
	v_sub_u32_e32 v0, v0, v1
	v_lshrrev_b32_e32 v1, 4, v0
	v_bitop3_b32 v1, v1, v0, 32 bitop3:0x6c
	v_ashrrev_i32_e32 v0, 31, v0
	v_lshrrev_b32_e32 v0, 26, v0
	s_waitcnt lgkmcnt(0)
	s_add_u32 s8, s4, 0x3214b200
	v_add_u32_e32 v0, v1, v0
	s_addc_u32 s9, s5, 0
	v_ashrrev_i32_e32 v12, 6, v0
	v_ashrrev_i32_e32 v0, 31, v8
	s_add_u32 s33, s4, 0x580000
	v_readlane_b32 s1, v253, 35
	v_lshrrev_b32_e32 v0, 26, v0
	s_addc_u32 s34, s5, 0
	s_ashr_i32 s14, s17, 6
	s_lshl_b32 s0, s1, 6
	v_add_u32_e32 v0, v8, v0
	s_ashr_i32 s15, s17, 8
	s_lshl_b32 s35, s14, 10
	s_or_b32 s0, s0, 2
	v_ashrrev_i32_e32 v13, 6, v0
	s_cmp_lt_i32 s1, 2
	s_mulk_i32 s1, 0x41
	v_lshlrev_b32_e32 v0, 3, v13
	v_and_b32_e32 v0, -16, v0
	s_cselect_b32 s0, s1, s0
	v_readlane_b32 s1, v253, 34
	v_add_u32_e32 v0, v12, v0
	s_add_i32 s0, s0, s1
	v_and_b32_e32 v3, 3, v12
	v_lshrrev_b32_e32 v4, 2, v0
	v_lshlrev_b32_e32 v5, 1, v0
	s_ashr_i32 s1, s0, 31
	v_and_or_b32 v3, v0, s10, v3
	v_and_b32_e32 v4, 4, v4
	v_and_b32_e32 v5, 24, v5
	s_lshr_b32 s1, s1, 28
	v_or3_b32 v3, v3, v4, v5
	v_mul_i32_i24_e32 v5, 64, v12
	s_add_i32 s1, s0, s1
	v_sub_u32_e32 v1, v1, v5
	s_ashr_i32 s10, s1, 4
	v_lshlrev_b32_e32 v4, 5, v13
	v_ashrrev_i16_sdwa v1, v2, sext(v1) dst_sel:DWORD dst_unused:UNUSED_PAD src0_sel:DWORD src1_sel:BYTE_0
	s_lshl_b32 s10, s10, 3
	v_and_b32_e32 v4, 32, v4
	v_bfe_i32 v14, v1, 0, 16
	s_sub_i32 s11, 0x101, s10
	v_add_lshl_u32 v1, v4, v14, 1
	s_min_u32 s11, s11, 8
	s_and_b32 s1, s1, -16
	v_lshl_add_u32 v148, v3, 10, v1
	s_sub_i32 s12, s0, s1
	v_cvt_f32_ubyte0_e32 v3, s11
	v_cvt_f32_i32_e32 v2, s12
	v_rcp_iflag_f32_e32 v4, v3
	v_lshl_add_u32 v150, v0, 10, v1
	s_ashr_i32 s0, s12, 30
	s_or_b32 s13, s0, 1
	v_mul_f32_e32 v0, v2, v4
	v_trunc_f32_e32 v0, v0
	v_fma_f32 v1, -v0, v3, v2
	v_cvt_i32_f32_e32 v0, v0
	v_cmp_ge_f32_e64 s[0:1], |v1|, v3
	s_and_b64 s[0:1], s[0:1], exec
	s_cselect_b32 s0, s13, 0
	v_readfirstlane_b32 s1, v0
	s_add_i32 s16, s1, s0
	s_mul_i32 s0, s16, s11
	s_sub_i32 s0, s12, s0
	s_sext_i32_i8 s0, s0
	s_add_i32 s0, s10, s0
	s_ashr_i32 s1, s0, 31
	s_bfe_i64 s[12:13], s[16:17], 0x80000
	s_lshl_b64 s[10:11], s[0:1], 18
	s_lshl_b64 s[12:13], s[12:13], 18
	s_add_u32 s28, s33, s12
	s_addc_u32 s29, s34, s13
	s_add_i32 s36, s35, 0
	s_add_i32 m0, s36, 0x10000
	v_mov_b32_e32 v149, 0
	global_load_lds_dwordx4 v148, s[28:29]
	s_add_i32 m0, s36, 0x12000
	s_add_u32 s12, s28, 0x20000
	global_load_lds_dwordx4 v144, s[28:29]
	s_addc_u32 s13, s29, 0
	s_add_i32 m0, s36, 0x14000
	v_mov_b32_e32 v145, v149
	global_load_lds_dwordx4 v148, s[12:13]
	s_add_i32 m0, s36, 0x16000
	s_add_u32 s26, s8, s10
	s_addc_u32 s27, s9, s11
	s_add_i32 s37, s36, 0x2000
	global_load_lds_dwordx4 v144, s[12:13]
	s_mov_b32 m0, s36
	s_add_u32 s10, s26, 0x20000
	global_load_lds_dwordx4 v150, s[26:27]
	s_mov_b32 m0, s37
	s_addc_u32 s11, s27, 0
	s_add_i32 s38, s36, 0x4000
	global_load_lds_dwordx4 v146, s[26:27]
	s_mov_b32 m0, s38
	s_add_i32 s39, s36, 0x6000
	global_load_lds_dwordx4 v150, s[10:11]
	s_mov_b32 m0, s39
	v_mov_b32_e32 v151, v149
	global_load_lds_dwordx4 v146, s[10:11]
	v_mov_b32_e32 v147, v149
	s_cmp_eq_u32 s15, 1
	s_mov_b32 s40, 0
	s_mov_b32 s101, 0xf
	s_mov_b32 s100, 0xf
	v_lshl_add_u64 v[6:7], s[28:29], 0, v[148:149]
	v_lshl_add_u64 v[4:5], s[28:29], 0, v[144:145]
	v_lshl_add_u64 v[0:1], s[26:27], 0, v[150:151]
	s_cselect_b64 s[10:11], -1, 0
	s_cmp_lg_u32 s15, 1
	v_lshl_add_u64 v[2:3], s[26:27], 0, v[146:147]
	s_cbranch_scc1 .LBB0_1394
	s_barrier

.LBB0_1396:
	s_mov_b32 s101, s100
	s_andn2_b64 vcc, exec, s[0:1]
	s_mov_b32 s1, s18
	s_mov_b32 s0, s20
	s_mov_b64 s[28:29], s[24:25]
	s_mov_b64 s[26:27], s[22:23]
	s_cbranch_vccz .LBB0_1410
.LBB0_1397:
	s_add_i32 s40, s40, 1
	s_mul_i32 s4, s40, s47
	s_mul_hi_u32 s5, s40, s46
	s_add_i32 s5, s5, s4
	s_mul_i32 s4, s40, s46
	s_add_u32 s22, s4, s94
	s_addc_u32 s23, s5, s95
	s_mov_b32 s100, 0xf
	s_cmp_eq_u32 s46, 0x100
	s_cbranch_scc0 .Lqs_done_5
	s_cmp_eq_u32 s40, 2
	s_cbranch_scc0 .Lqs_done_5
	s_mov_b32 s23, 0
	s_mov_b32 s22, 0x7fffffff
	s_cmp_lt_u32 s94, 8
	s_cbranch_scc0 .Lqs_done_5
	s_lshr_b32 s22, s94, 2
	s_add_i32 s22, s22, 0x200
	s_and_b32 s98, s94, 3
	s_lshl_b32 s100, 1, s98
	s_lshl_b32 s98, s98, 4
	s_or_b32 s100, s100, s98
	s_or_b32 s100, s100, 0x40
.Lqs_done_5:
	v_cmp_gt_i64_e32 vcc, s[22:23], v[158:159]
	v_cmp_lt_i64_e64 s[4:5], s[22:23], v[156:157]
	s_cbranch_vccnz .LBB0_1403
	s_ashr_i32 s18, s22, 31
	s_lshr_b32 s18, s18, 29
	s_add_i32 s20, s22, s18
	s_and_b32 s18, s20, -8
	s_sub_i32 s21, s22, s18
	s_cmp_gt_i32 s21, 1
	s_mov_b64 s[18:19], -1
	s_cbranch_scc0 .LBB0_1400
	s_lshl_b32 s18, s21, 6
	s_or_b32 s22, s18, 2
	s_mov_b64 s[18:19], 0

.LBB0_1404:
	ds_read_b128 v[128:131], v173
	ds_read_b128 v[132:135], v173 offset:1024
	ds_read_b128 v[136:139], v173 offset:2048
	ds_read_b128 v[140:143], v173 offset:3072
	ds_read_b128 v[160:163], v174
	ds_read_b128 v[164:167], v174 offset:1024
	ds_read_b128 v[168:171], v174 offset:2048
	ds_read_b128 v[176:179], v174 offset:3072
	s_add_u32 s28, s26, 0xfffe0080
	s_addc_u32 s29, s27, -1
	s_cmp_eq_u32 s53, 4
	s_cselect_b32 s31, s21, s29
	s_cselect_b32 s30, s44, s28
	s_cselect_b32 s29, s19, s52
	s_cselect_b32 s28, s45, s51
	v_lshl_add_u64 v[214:215], s[26:27], 0, v[152:153]
	s_add_i32 m0, s36, 0xc000
	ds_read_b128 v[182:185], v175
	ds_read_b128 v[186:189], v175 offset:1024
	ds_read_b128 v[190:193], v175 offset:2048
	ds_read_b128 v[194:197], v175 offset:3072
	ds_read_b128 v[198:201], v175 offset:4096
	ds_read_b128 v[202:205], v175 offset:5120
	ds_read_b128 v[206:209], v175 offset:6144
	ds_read_b128 v[210:213], v175 offset:7168
	global_load_lds_dwordx4 v[214:215], off
	v_lshl_add_u64 v[214:215], s[26:27], 0, v[154:155]
	s_add_i32 m0, s36, 0xe000
	s_nop 0
	global_load_lds_dwordx4 v[214:215], off
	s_waitcnt vmcnt(8)
	s_waitcnt lgkmcnt(0)
	s_barrier
	s_setprio 1
	s_waitcnt lgkmcnt(0)
	s_bitcmp1_b32 s101, 0
	s_cbranch_scc0 .Lmm_5_0
	v_mfma_f32_16x16x32_bf16 v[124:127], v[128:131], v[182:185], v[124:127]
	v_mfma_f32_16x16x32_bf16 v[120:123], v[136:139], v[182:185], v[120:123]
	v_mfma_f32_16x16x32_bf16 v[116:119], v[128:131], v[190:193], v[116:119]
	v_mfma_f32_16x16x32_bf16 v[112:115], v[136:139], v[190:193], v[112:115]
	v_mfma_f32_16x16x32_bf16 v[108:111], v[128:131], v[198:201], v[108:111]
	v_mfma_f32_16x16x32_bf16 v[104:107], v[136:139], v[198:201], v[104:107]
	v_mfma_f32_16x16x32_bf16 v[100:103], v[128:131], v[206:209], v[100:103]
	v_mfma_f32_16x16x32_bf16 v[96:99], v[136:139], v[206:209], v[96:99]
	v_mfma_f32_16x16x32_bf16 v[124:127], v[132:135], v[186:189], v[124:127]
	v_mfma_f32_16x16x32_bf16 v[120:123], v[140:143], v[186:189], v[120:123]
	v_mfma_f32_16x16x32_bf16 v[116:119], v[132:135], v[194:197], v[116:119]
	v_mfma_f32_16x16x32_bf16 v[112:115], v[140:143], v[194:197], v[112:115]
	v_mfma_f32_16x16x32_bf16 v[108:111], v[132:135], v[202:205], v[108:111]
	v_mfma_f32_16x16x32_bf16 v[104:107], v[140:143], v[202:205], v[104:107]
	v_mfma_f32_16x16x32_bf16 v[100:103], v[132:135], v[210:213], v[100:103]
	v_mfma_f32_16x16x32_bf16 v[96:99], v[140:143], v[210:213], v[96:99]
.Lmm_5_0:
	s_setprio 0
	s_setprio 1
	s_bitcmp1_b32 s101, 1
	s_cbranch_scc0 .Lmm_5_1
	v_mfma_f32_16x16x32_bf16 v[60:63], v[160:163], v[182:185], v[60:63]
	v_mfma_f32_16x16x32_bf16 v[56:59], v[168:171], v[182:185], v[56:59]
	v_mfma_f32_16x16x32_bf16 v[52:55], v[160:163], v[190:193], v[52:55]
	v_mfma_f32_16x16x32_bf16 v[48:51], v[168:171], v[190:193], v[48:51]
	v_mfma_f32_16x16x32_bf16 v[44:47], v[160:163], v[198:201], v[44:47]
	v_mfma_f32_16x16x32_bf16 v[40:43], v[168:171], v[198:201], v[40:43]
	v_mfma_f32_16x16x32_bf16 v[36:39], v[160:163], v[206:209], v[36:39]
	v_mfma_f32_16x16x32_bf16 v[32:35], v[168:171], v[206:209], v[32:35]
	v_mfma_f32_16x16x32_bf16 v[60:63], v[164:167], v[186:189], v[60:63]
	v_mfma_f32_16x16x32_bf16 v[56:59], v[176:179], v[186:189], v[56:59]
	v_mfma_f32_16x16x32_bf16 v[52:55], v[164:167], v[194:197], v[52:55]
	v_mfma_f32_16x16x32_bf16 v[48:51], v[176:179], v[194:197], v[48:51]
	v_mfma_f32_16x16x32_bf16 v[44:47], v[164:167], v[202:205], v[44:47]
	v_mfma_f32_16x16x32_bf16 v[40:43], v[176:179], v[202:205], v[40:43]
	v_mfma_f32_16x16x32_bf16 v[36:39], v[164:167], v[210:213], v[36:39]
	v_mfma_f32_16x16x32_bf16 v[32:35], v[176:179], v[210:213], v[32:35]
.Lmm_5_1:
	s_setprio 0
	s_barrier
	s_add_i32 s54, s49, s35
	v_lshl_add_u64 v[214:215], s[28:29], 0, v[148:149]
	s_mov_b32 m0, s54
	ds_read_b128 v[182:185], v175 offset:16384
	ds_read_b128 v[186:189], v175 offset:17408
	ds_read_b128 v[190:193], v175 offset:18432
	ds_read_b128 v[194:197], v175 offset:19456
	ds_read_b128 v[198:201], v175 offset:20480
	ds_read_b128 v[202:205], v175 offset:21504
	ds_read_b128 v[206:209], v175 offset:22528
	ds_read_b128 v[210:213], v175 offset:23552
	global_load_lds_dwordx4 v[214:215], off
	s_add_i32 m0, s54, 0x2000
	s_add_u32 s54, s28, 0x20000
	v_lshl_add_u64 v[216:217], s[28:29], 0, v[144:145]
	s_addc_u32 s55, s29, 0
	s_add_i32 s56, s50, s35
	global_load_lds_dwordx4 v[216:217], off
	v_lshl_add_u64 v[218:219], s[54:55], 0, v[148:149]
	s_mov_b32 m0, s56
	v_lshl_add_u64 v[220:221], s[30:31], 0, v[146:147]
	global_load_lds_dwordx4 v[218:219], off
	v_lshl_add_u64 v[218:219], s[54:55], 0, v[144:145]
	s_add_i32 m0, s56, 0x2000
	s_nop 0
	global_load_lds_dwordx4 v[218:219], off
	v_lshl_add_u64 v[218:219], s[30:31], 0, v[150:151]
	s_mov_b32 m0, s36
	s_nop 0
	global_load_lds_dwordx4 v[218:219], off
	s_mov_b32 m0, s37
	s_nop 0
	global_load_lds_dwordx4 v[220:221], off
	s_waitcnt vmcnt(8)
	s_waitcnt lgkmcnt(0)
	s_barrier
	s_setprio 1
	s_waitcnt lgkmcnt(0)
	s_bitcmp1_b32 s101, 2
	s_cbranch_scc0 .Lmm_5_2
	v_mfma_f32_16x16x32_bf16 v[92:95], v[128:131], v[182:185], v[92:95]
	v_mfma_f32_16x16x32_bf16 v[88:91], v[136:139], v[182:185], v[88:91]
	v_mfma_f32_16x16x32_bf16 v[84:87], v[128:131], v[190:193], v[84:87]
	v_mfma_f32_16x16x32_bf16 v[80:83], v[136:139], v[190:193], v[80:83]
	v_mfma_f32_16x16x32_bf16 v[76:79], v[128:131], v[198:201], v[76:79]
	v_mfma_f32_16x16x32_bf16 v[72:75], v[136:139], v[198:201], v[72:75]
	v_mfma_f32_16x16x32_bf16 v[68:71], v[128:131], v[206:209], v[68:71]
	v_mfma_f32_16x16x32_bf16 v[64:67], v[136:139], v[206:209], v[64:67]
	v_mfma_f32_16x16x32_bf16 v[92:95], v[132:135], v[186:189], v[92:95]
	v_mfma_f32_16x16x32_bf16 v[88:91], v[140:143], v[186:189], v[88:91]
	v_mfma_f32_16x16x32_bf16 v[84:87], v[132:135], v[194:197], v[84:87]
	v_mfma_f32_16x16x32_bf16 v[80:83], v[140:143], v[194:197], v[80:83]
	v_mfma_f32_16x16x32_bf16 v[76:79], v[132:135], v[202:205], v[76:79]
	v_mfma_f32_16x16x32_bf16 v[72:75], v[140:143], v[202:205], v[72:75]
	v_mfma_f32_16x16x32_bf16 v[68:71], v[132:135], v[210:213], v[68:71]
	v_mfma_f32_16x16x32_bf16 v[64:67], v[140:143], v[210:213], v[64:67]
.Lmm_5_2:
	s_setprio 0
	s_setprio 1
	s_bitcmp1_b32 s101, 3
	s_cbranch_scc0 .Lmm_5_3
	v_mfma_f32_16x16x32_bf16 v[28:31], v[160:163], v[182:185], v[28:31]
	v_mfma_f32_16x16x32_bf16 v[24:27], v[168:171], v[182:185], v[24:27]
	v_mfma_f32_16x16x32_bf16 v[20:23], v[160:163], v[190:193], v[20:23]
	v_mfma_f32_16x16x32_bf16 v[16:19], v[168:171], v[190:193], v[16:19]
	v_mfma_f32_16x16x32_bf16 v[12:15], v[160:163], v[198:201], v[12:15]
	v_mfma_f32_16x16x32_bf16 v[8:11], v[168:171], v[198:201], v[8:11]
	v_mfma_f32_16x16x32_bf16 v[4:7], v[160:163], v[206:209], v[4:7]
	v_mfma_f32_16x16x32_bf16 v[0:3], v[168:171], v[206:209], v[0:3]
	v_mfma_f32_16x16x32_bf16 v[28:31], v[164:167], v[186:189], v[28:31]
	v_mfma_f32_16x16x32_bf16 v[24:27], v[176:179], v[186:189], v[24:27]
	v_mfma_f32_16x16x32_bf16 v[20:23], v[164:167], v[194:197], v[20:23]
	v_mfma_f32_16x16x32_bf16 v[16:19], v[176:179], v[194:197], v[16:19]
	v_mfma_f32_16x16x32_bf16 v[12:15], v[164:167], v[202:205], v[12:15]
	v_mfma_f32_16x16x32_bf16 v[8:11], v[176:179], v[202:205], v[8:11]
	v_mfma_f32_16x16x32_bf16 v[4:7], v[164:167], v[210:213], v[4:7]
	v_mfma_f32_16x16x32_bf16 v[0:3], v[176:179], v[210:213], v[0:3]
.Lmm_5_3:
	s_setprio 0
	s_barrier
	s_add_i32 s54, 0, 0x18000
	s_add_i32 s55, 0, 0x1c000
	v_add_u32_e32 v140, s54, v172
	v_add_u32_e32 v176, s55, v172
	ds_read_b128 v[128:131], v140
	ds_read_b128 v[132:135], v140 offset:1024
	ds_read_b128 v[136:139], v140 offset:2048
	ds_read_b128 v[140:143], v140 offset:3072
	ds_read_b128 v[160:163], v176
	ds_read_b128 v[164:167], v176 offset:1024
	ds_read_b128 v[168:171], v176 offset:2048
	ds_read_b128 v[176:179], v176 offset:3072
	s_add_u32 s30, s30, 0x20000
	s_addc_u32 s31, s31, 0
	s_mov_b32 m0, s38
	v_lshl_add_u64 v[222:223], s[30:31], 0, v[150:151]
	ds_read_b128 v[182:185], v175 offset:32768
	ds_read_b128 v[186:189], v175 offset:33792
	ds_read_b128 v[190:193], v175 offset:34816
	ds_read_b128 v[194:197], v175 offset:35840
	ds_read_b128 v[198:201], v175 offset:36864
	ds_read_b128 v[202:205], v175 offset:37888
	ds_read_b128 v[206:209], v175 offset:38912
	ds_read_b128 v[210:213], v175 offset:39936
	global_load_lds_dwordx4 v[222:223], off
	v_lshl_add_u64 v[222:223], s[30:31], 0, v[146:147]
	s_mov_b32 m0, s39
	s_nop 0
	global_load_lds_dwordx4 v[222:223], off
	s_waitcnt vmcnt(8)
	s_waitcnt lgkmcnt(0)
	s_barrier
	s_setprio 1
	s_waitcnt lgkmcnt(0)
	s_bitcmp1_b32 s101, 0
	s_cbranch_scc0 .Lmm_5_4
	v_mfma_f32_16x16x32_bf16 v[124:127], v[128:131], v[182:185], v[124:127]
	v_mfma_f32_16x16x32_bf16 v[120:123], v[136:139], v[182:185], v[120:123]
	v_mfma_f32_16x16x32_bf16 v[116:119], v[128:131], v[190:193], v[116:119]
	v_mfma_f32_16x16x32_bf16 v[112:115], v[136:139], v[190:193], v[112:115]
	v_mfma_f32_16x16x32_bf16 v[108:111], v[128:131], v[198:201], v[108:111]
	v_mfma_f32_16x16x32_bf16 v[104:107], v[136:139], v[198:201], v[104:107]
	v_mfma_f32_16x16x32_bf16 v[100:103], v[128:131], v[206:209], v[100:103]
	v_mfma_f32_16x16x32_bf16 v[96:99], v[136:139], v[206:209], v[96:99]
	v_mfma_f32_16x16x32_bf16 v[124:127], v[132:135], v[186:189], v[124:127]
	v_mfma_f32_16x16x32_bf16 v[120:123], v[140:143], v[186:189], v[120:123]
	v_mfma_f32_16x16x32_bf16 v[116:119], v[132:135], v[194:197], v[116:119]
	v_mfma_f32_16x16x32_bf16 v[112:115], v[140:143], v[194:197], v[112:115]
	v_mfma_f32_16x16x32_bf16 v[108:111], v[132:135], v[202:205], v[108:111]
	v_mfma_f32_16x16x32_bf16 v[104:107], v[140:143], v[202:205], v[104:107]
	v_mfma_f32_16x16x32_bf16 v[100:103], v[132:135], v[210:213], v[100:103]
	v_mfma_f32_16x16x32_bf16 v[96:99], v[140:143], v[210:213], v[96:99]

.Lmm_5_5:
	s_setprio 0
	s_barrier
	s_add_i32 s30, s54, s35
	v_lshl_add_u64 v[214:215], v[214:215], 0, s[14:15]
	s_mov_b32 m0, s30
	ds_read_b128 v[182:185], v175 offset:49152
	ds_read_b128 v[186:189], v175 offset:50176
	ds_read_b128 v[190:193], v175 offset:51200
	ds_read_b128 v[194:197], v175 offset:52224
	ds_read_b128 v[198:201], v175 offset:53248
	ds_read_b128 v[202:205], v175 offset:54272
	ds_read_b128 v[206:209], v175 offset:55296
	ds_read_b128 v[210:213], v175 offset:56320
	global_load_lds_dwordx4 v[214:215], off
	s_add_i32 m0, s30, 0x2000
	s_add_u32 s28, s28, 0x20080
	v_lshl_add_u64 v[214:215], v[216:217], 0, s[14:15]
	s_addc_u32 s29, s29, 0
	s_add_i32 s30, s55, s35
	global_load_lds_dwordx4 v[214:215], off
	v_lshl_add_u64 v[214:215], s[28:29], 0, v[148:149]
	s_mov_b32 m0, s30
	s_nop 0
	global_load_lds_dwordx4 v[214:215], off
	v_lshl_add_u64 v[214:215], s[28:29], 0, v[144:145]
	s_add_i32 m0, s30, 0x2000
	s_nop 0
	global_load_lds_dwordx4 v[214:215], off
	v_lshl_add_u64 v[214:215], v[218:219], 0, s[14:15]
	s_mov_b32 m0, s43
	s_nop 0
	global_load_lds_dwordx4 v[214:215], off
	v_lshl_add_u64 v[214:215], v[220:221], 0, s[14:15]
	s_mov_b32 m0, s48
	s_nop 0
	global_load_lds_dwordx4 v[214:215], off
	s_waitcnt vmcnt(8)
	s_waitcnt lgkmcnt(0)
	s_barrier
	s_setprio 1
	s_waitcnt lgkmcnt(0)
	s_bitcmp1_b32 s101, 2
	s_cbranch_scc0 .Lmm_5_6
	v_mfma_f32_16x16x32_bf16 v[92:95], v[128:131], v[182:185], v[92:95]
	v_mfma_f32_16x16x32_bf16 v[88:91], v[136:139], v[182:185], v[88:91]
	v_mfma_f32_16x16x32_bf16 v[84:87], v[128:131], v[190:193], v[84:87]
	v_mfma_f32_16x16x32_bf16 v[80:83], v[136:139], v[190:193], v[80:83]
	v_mfma_f32_16x16x32_bf16 v[76:79], v[128:131], v[198:201], v[76:79]
	v_mfma_f32_16x16x32_bf16 v[72:75], v[136:139], v[198:201], v[72:75]
	v_mfma_f32_16x16x32_bf16 v[68:71], v[128:131], v[206:209], v[68:71]
	v_mfma_f32_16x16x32_bf16 v[64:67], v[136:139], v[206:209], v[64:67]
	v_mfma_f32_16x16x32_bf16 v[92:95], v[132:135], v[186:189], v[92:95]
	v_mfma_f32_16x16x32_bf16 v[88:91], v[140:143], v[186:189], v[88:91]
	v_mfma_f32_16x16x32_bf16 v[84:87], v[132:135], v[194:197], v[84:87]
	v_mfma_f32_16x16x32_bf16 v[80:83], v[140:143], v[194:197], v[80:83]
	v_mfma_f32_16x16x32_bf16 v[76:79], v[132:135], v[202:205], v[76:79]
	v_mfma_f32_16x16x32_bf16 v[72:75], v[140:143], v[202:205], v[72:75]
	v_mfma_f32_16x16x32_bf16 v[68:71], v[132:135], v[210:213], v[68:71]
	v_mfma_f32_16x16x32_bf16 v[64:67], v[140:143], v[210:213], v[64:67]

.Lmm_5_7:
	s_setprio 0
	s_barrier
	s_add_i32 s53, s53, 2
	s_add_u32 s26, s26, 0x100
	s_addc_u32 s27, s27, 0
	s_add_u32 s51, s51, 0x100
	s_addc_u32 s52, s52, 0
	s_cmp_gt_u32 s53, 5
	s_cbranch_scc0 .LBB0_1404
	s_and_b64 vcc, exec, s[16:17]
	s_cbranch_vccz .LBB0_1407
	s_barrier
.LBB0_1407:
	s_bitcmp1_b32 s101, 6
	s_cbranch_scc1 .Lqepi_5
	v_and_b32_e32 v128, 63, v180
	v_and_b32_e32 v129, 15, v180
	v_bfe_u32 v130, v180, 4, 2
	v_lshrrev_b32_e32 v131, 6, v180
	v_lshlrev_b32_e32 v131, 12, v131
	v_add_u32_e32 v131, 0x20000, v131
	v_and_b32_e32 v132, 7, v129
	v_lshlrev_b32_e32 v133, 1, v130
	v_xor_b32_e32 v132, v133, v132
	v_lshlrev_b32_e32 v132, 4, v132
	v_lshl_add_u32 v132, v129, 8, v132
	v_add_u32_e32 v160, v131, v132
	v_xor_b32_e32 v161, 16, v160
	v_lshrrev_b32_e32 v133, 2, v128
	v_and_b32_e32 v134, 3, v128
	v_and_b32_e32 v135, 7, v133
	v_lshlrev_b32_e32 v136, 1, v134
	v_xor_b32_e32 v136, v136, v135
	v_lshlrev_b32_e32 v136, 4, v136
	v_lshl_add_u32 v136, v133, 8, v136
	v_add_u32_e32 v162, v131, v136
	v_xor_b32_e32 v163, 16, v162
	s_lshl_b32 s0, s0, 8
	s_add_i32 s0, s0, s41
	v_add_u32_e32 v137, s0, v133
	s_lshl_b32 s1, s1, 8
	s_add_i32 s1, s1, s42
	v_lshl_add_u32 v138, v134, 3, s1
	v_lshlrev_b32_e32 v139, 10, v137
	v_lshl_add_u32 v164, v138, 1, v139
	v_lshlrev_b32_e32 v139, 11, v137
	v_lshl_add_u32 v165, v138, 1, v139
	v_lshlrev_b32_e32 v139, 2, v138
	v_mov_b32_e32 v170, 1.0
	v_mov_b32_e32 v171, 1.0
	v_mov_b32_e32 v176, 0xbfb8aa3b
	v_mov_b32_e32 v177, 0xbfb8aa3b
	global_load_dwordx4 v[184:187], v139, s[6:7]
	global_load_dwordx4 v[188:191], v139, s[6:7] offset:16
	global_load_dwordx4 v[192:195], v139, s[6:7] offset:512
	global_load_dwordx4 v[196:199], v139, s[6:7] offset:528
	s_mov_b64 s[98:99], s[8:9]
	global_load_dwordx4 v[200:203], v164, s[98:99]
	global_load_dwordx4 v[204:207], v164, s[98:99] offset:256
	s_add_u32 s98, s98, 0x4000
	s_addc_u32 s99, s99, 0
	global_load_dwordx4 v[208:211], v164, s[98:99]
	global_load_dwordx4 v[212:215], v164, s[98:99] offset:256
	s_add_u32 s98, s98, 0x4000
	s_addc_u32 s99, s99, 0
	global_load_dwordx4 v[216:219], v164, s[98:99]
	global_load_dwordx4 v[220:223], v164, s[98:99] offset:256
	s_add_u32 s98, s98, 0x4000
	s_addc_u32 s99, s99, 0
	global_load_dwordx4 v[224:227], v164, s[98:99]
	global_load_dwordx4 v[228:231], v164, s[98:99] offset:256
	s_add_u32 s98, s98, 0x14000
	s_addc_u32 s99, s99, 0
	ds_write_b128 v160, v[124:127]
	ds_write_b128 v161, v[120:123]
	ds_write_b128 v160, v[60:63] offset:128
	ds_write_b128 v161, v[56:59] offset:128
	s_waitcnt lgkmcnt(0)
	ds_read_b128 v[128:131], v162
	ds_read_b128 v[132:135], v163
	ds_read_b128 v[136:139], v162 offset:128
	ds_read_b128 v[140:143], v163 offset:128
	s_waitcnt vmcnt(6)
	s_waitcnt lgkmcnt(0)
	v_pk_add_f32 v[128:129], v[128:129], v[184:185]
	v_pk_add_f32 v[130:131], v[130:131], v[186:187]
	v_pk_add_f32 v[132:133], v[132:133], v[188:189]
	v_pk_add_f32 v[134:135], v[134:135], v[190:191]
	v_pk_mul_f32 v[128:129], v[128:129], v[176:177]
	v_pk_mul_f32 v[130:131], v[130:131], v[176:177]
	v_pk_mul_f32 v[132:133], v[132:133], v[176:177]
	v_pk_mul_f32 v[134:135], v[134:135], v[176:177]
	v_exp_f32_e32 v128, v128
	v_exp_f32_e32 v129, v129
	v_exp_f32_e32 v130, v130
	v_exp_f32_e32 v131, v131
	v_exp_f32_e32 v132, v132
	v_exp_f32_e32 v133, v133
	v_exp_f32_e32 v134, v134
	v_exp_f32_e32 v135, v135
	v_lshlrev_b32_e32 v232, 16, v200
	v_and_b32_e32 v233, 0xffff0000, v200
	v_lshlrev_b32_e32 v234, 16, v201
	v_and_b32_e32 v235, 0xffff0000, v201
	v_lshlrev_b32_e32 v236, 16, v202
	v_and_b32_e32 v237, 0xffff0000, v202
	v_lshlrev_b32_e32 v238, 16, v203
	v_and_b32_e32 v239, 0xffff0000, v203
	v_pk_add_f32 v[128:129], v[128:129], v[170:171]
	v_pk_add_f32 v[130:131], v[130:131], v[170:171]
	v_pk_add_f32 v[132:133], v[132:133], v[170:171]
	v_pk_add_f32 v[134:135], v[134:135], v[170:171]
	v_rcp_f32_e32 v128, v128
	v_rcp_f32_e32 v129, v129
	v_rcp_f32_e32 v130, v130
	v_rcp_f32_e32 v131, v131
	v_rcp_f32_e32 v132, v132
	v_rcp_f32_e32 v133, v133
	v_rcp_f32_e32 v134, v134
	v_rcp_f32_e32 v135, v135
	s_nop 0
	v_pk_mul_f32 v[128:129], v[128:129], v[232:233]
	v_pk_mul_f32 v[130:131], v[130:131], v[234:235]
	v_pk_mul_f32 v[132:133], v[132:133], v[236:237]
	v_pk_mul_f32 v[134:135], v[134:135], v[238:239]
	v_cvt_pk_bf16_f32 v248, v128, v129
	v_cvt_pk_bf16_f32 v249, v130, v131
	v_cvt_pk_bf16_f32 v250, v132, v133
	v_cvt_pk_bf16_f32 v251, v134, v135
	global_store_dwordx4 v165, v[248:251], s[12:13]
	v_pk_add_f32 v[136:137], v[136:137], v[192:193]
	v_pk_add_f32 v[138:139], v[138:139], v[194:195]
	v_pk_add_f32 v[140:141], v[140:141], v[196:197]
	v_pk_add_f32 v[142:143], v[142:143], v[198:199]
	v_pk_mul_f32 v[136:137], v[136:137], v[176:177]
	v_pk_mul_f32 v[138:139], v[138:139], v[176:177]
	v_pk_mul_f32 v[140:141], v[140:141], v[176:177]
	v_pk_mul_f32 v[142:143], v[142:143], v[176:177]
	v_exp_f32_e32 v136, v136
	v_exp_f32_e32 v137, v137
	v_exp_f32_e32 v138, v138
	v_exp_f32_e32 v139, v139
	v_exp_f32_e32 v140, v140
	v_exp_f32_e32 v141, v141
	v_exp_f32_e32 v142, v142
	v_exp_f32_e32 v143, v143
	v_lshlrev_b32_e32 v232, 16, v204
	v_and_b32_e32 v233, 0xffff0000, v204
	v_lshlrev_b32_e32 v234, 16, v205
	v_and_b32_e32 v235, 0xffff0000, v205
	v_lshlrev_b32_e32 v236, 16, v206
	v_and_b32_e32 v237, 0xffff0000, v206
	v_lshlrev_b32_e32 v238, 16, v207
	v_and_b32_e32 v239, 0xffff0000, v207
	v_pk_add_f32 v[136:137], v[136:137], v[170:171]
	v_pk_add_f32 v[138:139], v[138:139], v[170:171]
	v_pk_add_f32 v[140:141], v[140:141], v[170:171]
	v_pk_add_f32 v[142:143], v[142:143], v[170:171]
	v_rcp_f32_e32 v136, v136
	v_rcp_f32_e32 v137, v137
	v_rcp_f32_e32 v138, v138
	v_rcp_f32_e32 v139, v139
	v_rcp_f32_e32 v140, v140
	v_rcp_f32_e32 v141, v141
	v_rcp_f32_e32 v142, v142
	v_rcp_f32_e32 v143, v143
	s_nop 0
	v_pk_mul_f32 v[136:137], v[136:137], v[232:233]
	v_pk_mul_f32 v[138:139], v[138:139], v[234:235]
	v_pk_mul_f32 v[140:141], v[140:141], v[236:237]
	v_pk_mul_f32 v[142:143], v[142:143], v[238:239]
	v_cvt_pk_bf16_f32 v166, v136, v137
	v_cvt_pk_bf16_f32 v167, v138, v139
	v_cvt_pk_bf16_f32 v168, v140, v141
	v_cvt_pk_bf16_f32 v169, v142, v143
	global_store_dwordx4 v165, v[166:169], s[12:13] offset:256
	global_load_dwordx4 v[200:203], v164, s[98:99]
	global_load_dwordx4 v[204:207], v164, s[98:99] offset:256
	s_add_u32 s98, s98, 0x4000
	s_addc_u32 s99, s99, 0
	v_add_u32_e32 v165, 0x8000, v165
	ds_write_b128 v160, v[116:119]
	ds_write_b128 v161, v[112:115]
	ds_write_b128 v160, v[52:55] offset:128
	ds_write_b128 v161, v[48:51] offset:128
	s_waitcnt lgkmcnt(0)
	ds_read_b128 v[128:131], v162
	ds_read_b128 v[132:135], v163
	ds_read_b128 v[136:139], v162 offset:128
	ds_read_b128 v[140:143], v163 offset:128
	s_waitcnt vmcnt(8)
	s_waitcnt lgkmcnt(0)
	v_pk_add_f32 v[128:129], v[128:129], v[184:185]
	v_pk_add_f32 v[130:131], v[130:131], v[186:187]
	v_pk_add_f32 v[132:133], v[132:133], v[188:189]
	v_pk_add_f32 v[134:135], v[134:135], v[190:191]
	v_pk_mul_f32 v[128:129], v[128:129], v[176:177]
	v_pk_mul_f32 v[130:131], v[130:131], v[176:177]
	v_pk_mul_f32 v[132:133], v[132:133], v[176:177]
	v_pk_mul_f32 v[134:135], v[134:135], v[176:177]
	v_exp_f32_e32 v128, v128
	v_exp_f32_e32 v129, v129
	v_exp_f32_e32 v130, v130
	v_exp_f32_e32 v131, v131
	v_exp_f32_e32 v132, v132
	v_exp_f32_e32 v133, v133
	v_exp_f32_e32 v134, v134
	v_exp_f32_e32 v135, v135
	v_lshlrev_b32_e32 v232, 16, v208
	v_and_b32_e32 v233, 0xffff0000, v208
	v_lshlrev_b32_e32 v234, 16, v209
	v_and_b32_e32 v235, 0xffff0000, v209
	v_lshlrev_b32_e32 v236, 16, v210
	v_and_b32_e32 v237, 0xffff0000, v210
	v_lshlrev_b32_e32 v238, 16, v211
	v_and_b32_e32 v239, 0xffff0000, v211
	v_pk_add_f32 v[128:129], v[128:129], v[170:171]
	v_pk_add_f32 v[130:131], v[130:131], v[170:171]
	v_pk_add_f32 v[132:133], v[132:133], v[170:171]
	v_pk_add_f32 v[134:135], v[134:135], v[170:171]
	v_rcp_f32_e32 v128, v128
	v_rcp_f32_e32 v129, v129
	v_rcp_f32_e32 v130, v130
	v_rcp_f32_e32 v131, v131
	v_rcp_f32_e32 v132, v132
	v_rcp_f32_e32 v133, v133
	v_rcp_f32_e32 v134, v134
	v_rcp_f32_e32 v135, v135
	s_nop 0
	v_pk_mul_f32 v[128:129], v[128:129], v[232:233]
	v_pk_mul_f32 v[130:131], v[130:131], v[234:235]
	v_pk_mul_f32 v[132:133], v[132:133], v[236:237]
	v_pk_mul_f32 v[134:135], v[134:135], v[238:239]
	v_cvt_pk_bf16_f32 v248, v128, v129
	v_cvt_pk_bf16_f32 v249, v130, v131
	v_cvt_pk_bf16_f32 v250, v132, v133
	v_cvt_pk_bf16_f32 v251, v134, v135
	global_store_dwordx4 v165, v[248:251], s[12:13]
	v_pk_add_f32 v[136:137], v[136:137], v[192:193]
	v_pk_add_f32 v[138:139], v[138:139], v[194:195]
	v_pk_add_f32 v[140:141], v[140:141], v[196:197]
	v_pk_add_f32 v[142:143], v[142:143], v[198:199]
	v_pk_mul_f32 v[136:137], v[136:137], v[176:177]
	v_pk_mul_f32 v[138:139], v[138:139], v[176:177]
	v_pk_mul_f32 v[140:141], v[140:141], v[176:177]
	v_pk_mul_f32 v[142:143], v[142:143], v[176:177]
	v_exp_f32_e32 v136, v136
	v_exp_f32_e32 v137, v137
	v_exp_f32_e32 v138, v138
	v_exp_f32_e32 v139, v139
	v_exp_f32_e32 v140, v140
	v_exp_f32_e32 v141, v141
	v_exp_f32_e32 v142, v142
	v_exp_f32_e32 v143, v143
	v_lshlrev_b32_e32 v232, 16, v212
	v_and_b32_e32 v233, 0xffff0000, v212
	v_lshlrev_b32_e32 v234, 16, v213
	v_and_b32_e32 v235, 0xffff0000, v213
	v_lshlrev_b32_e32 v236, 16, v214
	v_and_b32_e32 v237, 0xffff0000, v214
	v_lshlrev_b32_e32 v238, 16, v215
	v_and_b32_e32 v239, 0xffff0000, v215
	v_pk_add_f32 v[136:137], v[136:137], v[170:171]
	v_pk_add_f32 v[138:139], v[138:139], v[170:171]
	v_pk_add_f32 v[140:141], v[140:141], v[170:171]
	v_pk_add_f32 v[142:143], v[142:143], v[170:171]
	v_rcp_f32_e32 v136, v136
	v_rcp_f32_e32 v137, v137
	v_rcp_f32_e32 v138, v138
	v_rcp_f32_e32 v139, v139
	v_rcp_f32_e32 v140, v140
	v_rcp_f32_e32 v141, v141
	v_rcp_f32_e32 v142, v142
	v_rcp_f32_e32 v143, v143
	s_nop 0
	v_pk_mul_f32 v[136:137], v[136:137], v[232:233]
	v_pk_mul_f32 v[138:139], v[138:139], v[234:235]
	v_pk_mul_f32 v[140:141], v[140:141], v[236:237]
	v_pk_mul_f32 v[142:143], v[142:143], v[238:239]
	v_cvt_pk_bf16_f32 v166, v136, v137
	v_cvt_pk_bf16_f32 v167, v138, v139
	v_cvt_pk_bf16_f32 v168, v140, v141
	v_cvt_pk_bf16_f32 v169, v142, v143
	global_store_dwordx4 v165, v[166:169], s[12:13] offset:256
	global_load_dwordx4 v[208:211], v164, s[98:99]
	global_load_dwordx4 v[212:215], v164, s[98:99] offset:256
	s_add_u32 s98, s98, 0x4000
	s_addc_u32 s99, s99, 0
	v_add_u32_e32 v165, 0x8000, v165
	ds_write_b128 v160, v[108:111]
	ds_write_b128 v161, v[104:107]
	ds_write_b128 v160, v[44:47] offset:128
	ds_write_b128 v161, v[40:43] offset:128
	s_waitcnt lgkmcnt(0)
	ds_read_b128 v[128:131], v162
	ds_read_b128 v[132:135], v163
	ds_read_b128 v[136:139], v162 offset:128
	ds_read_b128 v[140:143], v163 offset:128
	s_waitcnt vmcnt(10)
	s_waitcnt lgkmcnt(0)
	v_pk_add_f32 v[128:129], v[128:129], v[184:185]
	v_pk_add_f32 v[130:131], v[130:131], v[186:187]
	v_pk_add_f32 v[132:133], v[132:133], v[188:189]
	v_pk_add_f32 v[134:135], v[134:135], v[190:191]
	v_pk_mul_f32 v[128:129], v[128:129], v[176:177]
	v_pk_mul_f32 v[130:131], v[130:131], v[176:177]
	v_pk_mul_f32 v[132:133], v[132:133], v[176:177]
	v_pk_mul_f32 v[134:135], v[134:135], v[176:177]
	v_exp_f32_e32 v128, v128
	v_exp_f32_e32 v129, v129
	v_exp_f32_e32 v130, v130
	v_exp_f32_e32 v131, v131
	v_exp_f32_e32 v132, v132
	v_exp_f32_e32 v133, v133
	v_exp_f32_e32 v134, v134
	v_exp_f32_e32 v135, v135
	v_lshlrev_b32_e32 v232, 16, v216
	v_and_b32_e32 v233, 0xffff0000, v216
	v_lshlrev_b32_e32 v234, 16, v217
	v_and_b32_e32 v235, 0xffff0000, v217
	v_lshlrev_b32_e32 v236, 16, v218
	v_and_b32_e32 v237, 0xffff0000, v218
	v_lshlrev_b32_e32 v238, 16, v219
	v_and_b32_e32 v239, 0xffff0000, v219
	v_pk_add_f32 v[128:129], v[128:129], v[170:171]
	v_pk_add_f32 v[130:131], v[130:131], v[170:171]
	v_pk_add_f32 v[132:133], v[132:133], v[170:171]
	v_pk_add_f32 v[134:135], v[134:135], v[170:171]
	v_rcp_f32_e32 v128, v128
	v_rcp_f32_e32 v129, v129
	v_rcp_f32_e32 v130, v130
	v_rcp_f32_e32 v131, v131
	v_rcp_f32_e32 v132, v132
	v_rcp_f32_e32 v133, v133
	v_rcp_f32_e32 v134, v134
	v_rcp_f32_e32 v135, v135
	s_nop 0
	v_pk_mul_f32 v[128:129], v[128:129], v[232:233]
	v_pk_mul_f32 v[130:131], v[130:131], v[234:235]
	v_pk_mul_f32 v[132:133], v[132:133], v[236:237]
	v_pk_mul_f32 v[134:135], v[134:135], v[238:239]
	v_cvt_pk_bf16_f32 v248, v128, v129
	v_cvt_pk_bf16_f32 v249, v130, v131
	v_cvt_pk_bf16_f32 v250, v132, v133
	v_cvt_pk_bf16_f32 v251, v134, v135
	global_store_dwordx4 v165, v[248:251], s[12:13]
	v_pk_add_f32 v[136:137], v[136:137], v[192:193]
	v_pk_add_f32 v[138:139], v[138:139], v[194:195]
	v_pk_add_f32 v[140:141], v[140:141], v[196:197]
	v_pk_add_f32 v[142:143], v[142:143], v[198:199]
	v_pk_mul_f32 v[136:137], v[136:137], v[176:177]
	v_pk_mul_f32 v[138:139], v[138:139], v[176:177]
	v_pk_mul_f32 v[140:141], v[140:141], v[176:177]
	v_pk_mul_f32 v[142:143], v[142:143], v[176:177]
	v_exp_f32_e32 v136, v136
	v_exp_f32_e32 v137, v137
	v_exp_f32_e32 v138, v138
	v_exp_f32_e32 v139, v139
	v_exp_f32_e32 v140, v140
	v_exp_f32_e32 v141, v141
	v_exp_f32_e32 v142, v142
	v_exp_f32_e32 v143, v143
	v_lshlrev_b32_e32 v232, 16, v220
	v_and_b32_e32 v233, 0xffff0000, v220
	v_lshlrev_b32_e32 v234, 16, v221
	v_and_b32_e32 v235, 0xffff0000, v221
	v_lshlrev_b32_e32 v236, 16, v222
	v_and_b32_e32 v237, 0xffff0000, v222
	v_lshlrev_b32_e32 v238, 16, v223
	v_and_b32_e32 v239, 0xffff0000, v223
	v_pk_add_f32 v[136:137], v[136:137], v[170:171]
	v_pk_add_f32 v[138:139], v[138:139], v[170:171]
	v_pk_add_f32 v[140:141], v[140:141], v[170:171]
	v_pk_add_f32 v[142:143], v[142:143], v[170:171]
	v_rcp_f32_e32 v136, v136
	v_rcp_f32_e32 v137, v137
	v_rcp_f32_e32 v138, v138
	v_rcp_f32_e32 v139, v139
	v_rcp_f32_e32 v140, v140
	v_rcp_f32_e32 v141, v141
	v_rcp_f32_e32 v142, v142
	v_rcp_f32_e32 v143, v143
	s_nop 0
	v_pk_mul_f32 v[136:137], v[136:137], v[232:233]
	v_pk_mul_f32 v[138:139], v[138:139], v[234:235]
	v_pk_mul_f32 v[140:141], v[140:141], v[236:237]
	v_pk_mul_f32 v[142:143], v[142:143], v[238:239]
	v_cvt_pk_bf16_f32 v166, v136, v137
	v_cvt_pk_bf16_f32 v167, v138, v139
	v_cvt_pk_bf16_f32 v168, v140, v141
	v_cvt_pk_bf16_f32 v169, v142, v143
	global_store_dwordx4 v165, v[166:169], s[12:13] offset:256
	global_load_dwordx4 v[216:219], v164, s[98:99]
	global_load_dwordx4 v[220:223], v164, s[98:99] offset:256
	s_add_u32 s98, s98, 0x4000
	s_addc_u32 s99, s99, 0
	v_add_u32_e32 v165, 0x8000, v165
	ds_write_b128 v160, v[100:103]
	ds_write_b128 v161, v[96:99]
	ds_write_b128 v160, v[36:39] offset:128
	ds_write_b128 v161, v[32:35] offset:128
	s_waitcnt lgkmcnt(0)
	ds_read_b128 v[128:131], v162
	ds_read_b128 v[132:135], v163
	ds_read_b128 v[136:139], v162 offset:128
	ds_read_b128 v[140:143], v163 offset:128
	s_waitcnt vmcnt(12)
	s_waitcnt lgkmcnt(0)
	v_pk_add_f32 v[128:129], v[128:129], v[184:185]
	v_pk_add_f32 v[130:131], v[130:131], v[186:187]
	v_pk_add_f32 v[132:133], v[132:133], v[188:189]
	v_pk_add_f32 v[134:135], v[134:135], v[190:191]
	v_pk_mul_f32 v[128:129], v[128:129], v[176:177]
	v_pk_mul_f32 v[130:131], v[130:131], v[176:177]
	v_pk_mul_f32 v[132:133], v[132:133], v[176:177]
	v_pk_mul_f32 v[134:135], v[134:135], v[176:177]
	v_exp_f32_e32 v128, v128
	v_exp_f32_e32 v129, v129
	v_exp_f32_e32 v130, v130
	v_exp_f32_e32 v131, v131
	v_exp_f32_e32 v132, v132
	v_exp_f32_e32 v133, v133
	v_exp_f32_e32 v134, v134
	v_exp_f32_e32 v135, v135
	v_lshlrev_b32_e32 v232, 16, v224
	v_and_b32_e32 v233, 0xffff0000, v224
	v_lshlrev_b32_e32 v234, 16, v225
	v_and_b32_e32 v235, 0xffff0000, v225
	v_lshlrev_b32_e32 v236, 16, v226
	v_and_b32_e32 v237, 0xffff0000, v226
	v_lshlrev_b32_e32 v238, 16, v227
	v_and_b32_e32 v239, 0xffff0000, v227
	v_pk_add_f32 v[128:129], v[128:129], v[170:171]
	v_pk_add_f32 v[130:131], v[130:131], v[170:171]
	v_pk_add_f32 v[132:133], v[132:133], v[170:171]
	v_pk_add_f32 v[134:135], v[134:135], v[170:171]
	v_rcp_f32_e32 v128, v128
	v_rcp_f32_e32 v129, v129
	v_rcp_f32_e32 v130, v130
	v_rcp_f32_e32 v131, v131
	v_rcp_f32_e32 v132, v132
	v_rcp_f32_e32 v133, v133
	v_rcp_f32_e32 v134, v134
	v_rcp_f32_e32 v135, v135
	s_nop 0
	v_pk_mul_f32 v[128:129], v[128:129], v[232:233]
	v_pk_mul_f32 v[130:131], v[130:131], v[234:235]
	v_pk_mul_f32 v[132:133], v[132:133], v[236:237]
	v_pk_mul_f32 v[134:135], v[134:135], v[238:239]
	v_cvt_pk_bf16_f32 v248, v128, v129
	v_cvt_pk_bf16_f32 v249, v130, v131
	v_cvt_pk_bf16_f32 v250, v132, v133
	v_cvt_pk_bf16_f32 v251, v134, v135
	global_store_dwordx4 v165, v[248:251], s[12:13]
	v_pk_add_f32 v[136:137], v[136:137], v[192:193]
	v_pk_add_f32 v[138:139], v[138:139], v[194:195]
	v_pk_add_f32 v[140:141], v[140:141], v[196:197]
	v_pk_add_f32 v[142:143], v[142:143], v[198:199]
	v_pk_mul_f32 v[136:137], v[136:137], v[176:177]
	v_pk_mul_f32 v[138:139], v[138:139], v[176:177]
	v_pk_mul_f32 v[140:141], v[140:141], v[176:177]
	v_pk_mul_f32 v[142:143], v[142:143], v[176:177]
	v_exp_f32_e32 v136, v136
	v_exp_f32_e32 v137, v137
	v_exp_f32_e32 v138, v138
	v_exp_f32_e32 v139, v139
	v_exp_f32_e32 v140, v140
	v_exp_f32_e32 v141, v141
	v_exp_f32_e32 v142, v142
	v_exp_f32_e32 v143, v143
	v_lshlrev_b32_e32 v232, 16, v228
	v_and_b32_e32 v233, 0xffff0000, v228
	v_lshlrev_b32_e32 v234, 16, v229
	v_and_b32_e32 v235, 0xffff0000, v229
	v_lshlrev_b32_e32 v236, 16, v230
	v_and_b32_e32 v237, 0xffff0000, v230
	v_lshlrev_b32_e32 v238, 16, v231
	v_and_b32_e32 v239, 0xffff0000, v231
	v_pk_add_f32 v[136:137], v[136:137], v[170:171]
	v_pk_add_f32 v[138:139], v[138:139], v[170:171]
	v_pk_add_f32 v[140:141], v[140:141], v[170:171]
	v_pk_add_f32 v[142:143], v[142:143], v[170:171]
	v_rcp_f32_e32 v136, v136
	v_rcp_f32_e32 v137, v137
	v_rcp_f32_e32 v138, v138
	v_rcp_f32_e32 v139, v139
	v_rcp_f32_e32 v140, v140
	v_rcp_f32_e32 v141, v141
	v_rcp_f32_e32 v142, v142
	v_rcp_f32_e32 v143, v143
	s_nop 0
	v_pk_mul_f32 v[136:137], v[136:137], v[232:233]
	v_pk_mul_f32 v[138:139], v[138:139], v[234:235]
	v_pk_mul_f32 v[140:141], v[140:141], v[236:237]
	v_pk_mul_f32 v[142:143], v[142:143], v[238:239]
	v_cvt_pk_bf16_f32 v166, v136, v137
	v_cvt_pk_bf16_f32 v167, v138, v139
	v_cvt_pk_bf16_f32 v168, v140, v141
	v_cvt_pk_bf16_f32 v169, v142, v143
	global_store_dwordx4 v165, v[166:169], s[12:13] offset:256
	global_load_dwordx4 v[224:227], v164, s[98:99]
	global_load_dwordx4 v[228:231], v164, s[98:99] offset:256
	v_add_u32_e32 v165, 0x28000, v165
	ds_write_b128 v160, v[92:95]
	ds_write_b128 v161, v[88:91]
	ds_write_b128 v160, v[28:31] offset:128
	ds_write_b128 v161, v[24:27] offset:128
	s_waitcnt lgkmcnt(0)
	ds_read_b128 v[128:131], v162
	ds_read_b128 v[132:135], v163
	ds_read_b128 v[136:139], v162 offset:128
	ds_read_b128 v[140:143], v163 offset:128
	s_waitcnt vmcnt(12)
	s_waitcnt lgkmcnt(0)
	v_pk_add_f32 v[128:129], v[128:129], v[184:185]
	v_pk_add_f32 v[130:131], v[130:131], v[186:187]
	v_pk_add_f32 v[132:133], v[132:133], v[188:189]
	v_pk_add_f32 v[134:135], v[134:135], v[190:191]
	v_pk_mul_f32 v[128:129], v[128:129], v[176:177]
	v_pk_mul_f32 v[130:131], v[130:131], v[176:177]
	v_pk_mul_f32 v[132:133], v[132:133], v[176:177]
	v_pk_mul_f32 v[134:135], v[134:135], v[176:177]
	v_exp_f32_e32 v128, v128
	v_exp_f32_e32 v129, v129
	v_exp_f32_e32 v130, v130
	v_exp_f32_e32 v131, v131
	v_exp_f32_e32 v132, v132
	v_exp_f32_e32 v133, v133
	v_exp_f32_e32 v134, v134
	v_exp_f32_e32 v135, v135
	v_lshlrev_b32_e32 v232, 16, v200
	v_and_b32_e32 v233, 0xffff0000, v200
	v_lshlrev_b32_e32 v234, 16, v201
	v_and_b32_e32 v235, 0xffff0000, v201
	v_lshlrev_b32_e32 v236, 16, v202
	v_and_b32_e32 v237, 0xffff0000, v202
	v_lshlrev_b32_e32 v238, 16, v203
	v_and_b32_e32 v239, 0xffff0000, v203
	v_pk_add_f32 v[128:129], v[128:129], v[170:171]
	v_pk_add_f32 v[130:131], v[130:131], v[170:171]
	v_pk_add_f32 v[132:133], v[132:133], v[170:171]
	v_pk_add_f32 v[134:135], v[134:135], v[170:171]
	v_rcp_f32_e32 v128, v128
	v_rcp_f32_e32 v129, v129
	v_rcp_f32_e32 v130, v130
	v_rcp_f32_e32 v131, v131
	v_rcp_f32_e32 v132, v132
	v_rcp_f32_e32 v133, v133
	v_rcp_f32_e32 v134, v134
	v_rcp_f32_e32 v135, v135
	s_nop 0
	v_pk_mul_f32 v[128:129], v[128:129], v[232:233]
	v_pk_mul_f32 v[130:131], v[130:131], v[234:235]
	v_pk_mul_f32 v[132:133], v[132:133], v[236:237]
	v_pk_mul_f32 v[134:135], v[134:135], v[238:239]
	v_cvt_pk_bf16_f32 v248, v128, v129
	v_cvt_pk_bf16_f32 v249, v130, v131
	v_cvt_pk_bf16_f32 v250, v132, v133
	v_cvt_pk_bf16_f32 v251, v134, v135
	global_store_dwordx4 v165, v[248:251], s[12:13]
	v_pk_add_f32 v[136:137], v[136:137], v[192:193]
	v_pk_add_f32 v[138:139], v[138:139], v[194:195]
	v_pk_add_f32 v[140:141], v[140:141], v[196:197]
	v_pk_add_f32 v[142:143], v[142:143], v[198:199]
	v_pk_mul_f32 v[136:137], v[136:137], v[176:177]
	v_pk_mul_f32 v[138:139], v[138:139], v[176:177]
	v_pk_mul_f32 v[140:141], v[140:141], v[176:177]
	v_pk_mul_f32 v[142:143], v[142:143], v[176:177]
	v_exp_f32_e32 v136, v136
	v_exp_f32_e32 v137, v137
	v_exp_f32_e32 v138, v138
	v_exp_f32_e32 v139, v139
	v_exp_f32_e32 v140, v140
	v_exp_f32_e32 v141, v141
	v_exp_f32_e32 v142, v142
	v_exp_f32_e32 v143, v143
	v_lshlrev_b32_e32 v232, 16, v204
	v_and_b32_e32 v233, 0xffff0000, v204
	v_lshlrev_b32_e32 v234, 16, v205
	v_and_b32_e32 v235, 0xffff0000, v205
	v_lshlrev_b32_e32 v236, 16, v206
	v_and_b32_e32 v237, 0xffff0000, v206
	v_lshlrev_b32_e32 v238, 16, v207
	v_and_b32_e32 v239, 0xffff0000, v207
	v_pk_add_f32 v[136:137], v[136:137], v[170:171]
	v_pk_add_f32 v[138:139], v[138:139], v[170:171]
	v_pk_add_f32 v[140:141], v[140:141], v[170:171]
	v_pk_add_f32 v[142:143], v[142:143], v[170:171]
	v_rcp_f32_e32 v136, v136
	v_rcp_f32_e32 v137, v137
	v_rcp_f32_e32 v138, v138
	v_rcp_f32_e32 v139, v139
	v_rcp_f32_e32 v140, v140
	v_rcp_f32_e32 v141, v141
	v_rcp_f32_e32 v142, v142
	v_rcp_f32_e32 v143, v143
	s_nop 0
	v_pk_mul_f32 v[136:137], v[136:137], v[232:233]
	v_pk_mul_f32 v[138:139], v[138:139], v[234:235]
	v_pk_mul_f32 v[140:141], v[140:141], v[236:237]
	v_pk_mul_f32 v[142:143], v[142:143], v[238:239]
	v_cvt_pk_bf16_f32 v166, v136, v137
	v_cvt_pk_bf16_f32 v167, v138, v139
	v_cvt_pk_bf16_f32 v168, v140, v141
	v_cvt_pk_bf16_f32 v169, v142, v143
	global_store_dwordx4 v165, v[166:169], s[12:13] offset:256
	v_add_u32_e32 v165, 0x8000, v165
	ds_write_b128 v160, v[84:87]
	ds_write_b128 v161, v[80:83]
	ds_write_b128 v160, v[20:23] offset:128
	ds_write_b128 v161, v[16:19] offset:128
	s_waitcnt lgkmcnt(0)
	ds_read_b128 v[128:131], v162
	ds_read_b128 v[132:135], v163
	ds_read_b128 v[136:139], v162 offset:128
	ds_read_b128 v[140:143], v163 offset:128
	s_waitcnt vmcnt(10)
	s_waitcnt lgkmcnt(0)
	v_pk_add_f32 v[128:129], v[128:129], v[184:185]
	v_pk_add_f32 v[130:131], v[130:131], v[186:187]
	v_pk_add_f32 v[132:133], v[132:133], v[188:189]
	v_pk_add_f32 v[134:135], v[134:135], v[190:191]
	v_pk_mul_f32 v[128:129], v[128:129], v[176:177]
	v_pk_mul_f32 v[130:131], v[130:131], v[176:177]
	v_pk_mul_f32 v[132:133], v[132:133], v[176:177]
	v_pk_mul_f32 v[134:135], v[134:135], v[176:177]
	v_exp_f32_e32 v128, v128
	v_exp_f32_e32 v129, v129
	v_exp_f32_e32 v130, v130
	v_exp_f32_e32 v131, v131
	v_exp_f32_e32 v132, v132
	v_exp_f32_e32 v133, v133
	v_exp_f32_e32 v134, v134
	v_exp_f32_e32 v135, v135
	v_lshlrev_b32_e32 v232, 16, v208
	v_and_b32_e32 v233, 0xffff0000, v208
	v_lshlrev_b32_e32 v234, 16, v209
	v_and_b32_e32 v235, 0xffff0000, v209
	v_lshlrev_b32_e32 v236, 16, v210
	v_and_b32_e32 v237, 0xffff0000, v210
	v_lshlrev_b32_e32 v238, 16, v211
	v_and_b32_e32 v239, 0xffff0000, v211
	v_pk_add_f32 v[128:129], v[128:129], v[170:171]
	v_pk_add_f32 v[130:131], v[130:131], v[170:171]
	v_pk_add_f32 v[132:133], v[132:133], v[170:171]
	v_pk_add_f32 v[134:135], v[134:135], v[170:171]
	v_rcp_f32_e32 v128, v128
	v_rcp_f32_e32 v129, v129
	v_rcp_f32_e32 v130, v130
	v_rcp_f32_e32 v131, v131
	v_rcp_f32_e32 v132, v132
	v_rcp_f32_e32 v133, v133
	v_rcp_f32_e32 v134, v134
	v_rcp_f32_e32 v135, v135
	s_nop 0
	v_pk_mul_f32 v[128:129], v[128:129], v[232:233]
	v_pk_mul_f32 v[130:131], v[130:131], v[234:235]
	v_pk_mul_f32 v[132:133], v[132:133], v[236:237]
	v_pk_mul_f32 v[134:135], v[134:135], v[238:239]
	v_cvt_pk_bf16_f32 v248, v128, v129
	v_cvt_pk_bf16_f32 v249, v130, v131
	v_cvt_pk_bf16_f32 v250, v132, v133
	v_cvt_pk_bf16_f32 v251, v134, v135
	global_store_dwordx4 v165, v[248:251], s[12:13]
	v_pk_add_f32 v[136:137], v[136:137], v[192:193]
	v_pk_add_f32 v[138:139], v[138:139], v[194:195]
	v_pk_add_f32 v[140:141], v[140:141], v[196:197]
	v_pk_add_f32 v[142:143], v[142:143], v[198:199]
	v_pk_mul_f32 v[136:137], v[136:137], v[176:177]
	v_pk_mul_f32 v[138:139], v[138:139], v[176:177]
	v_pk_mul_f32 v[140:141], v[140:141], v[176:177]
	v_pk_mul_f32 v[142:143], v[142:143], v[176:177]
	v_exp_f32_e32 v136, v136
	v_exp_f32_e32 v137, v137
	v_exp_f32_e32 v138, v138
	v_exp_f32_e32 v139, v139
	v_exp_f32_e32 v140, v140
	v_exp_f32_e32 v141, v141
	v_exp_f32_e32 v142, v142
	v_exp_f32_e32 v143, v143
	v_lshlrev_b32_e32 v232, 16, v212
	v_and_b32_e32 v233, 0xffff0000, v212
	v_lshlrev_b32_e32 v234, 16, v213
	v_and_b32_e32 v235, 0xffff0000, v213
	v_lshlrev_b32_e32 v236, 16, v214
	v_and_b32_e32 v237, 0xffff0000, v214
	v_lshlrev_b32_e32 v238, 16, v215
	v_and_b32_e32 v239, 0xffff0000, v215
	v_pk_add_f32 v[136:137], v[136:137], v[170:171]
	v_pk_add_f32 v[138:139], v[138:139], v[170:171]
	v_pk_add_f32 v[140:141], v[140:141], v[170:171]
	v_pk_add_f32 v[142:143], v[142:143], v[170:171]
	v_rcp_f32_e32 v136, v136
	v_rcp_f32_e32 v137, v137
	v_rcp_f32_e32 v138, v138
	v_rcp_f32_e32 v139, v139
	v_rcp_f32_e32 v140, v140
	v_rcp_f32_e32 v141, v141
	v_rcp_f32_e32 v142, v142
	v_rcp_f32_e32 v143, v143
	s_nop 0
	v_pk_mul_f32 v[136:137], v[136:137], v[232:233]
	v_pk_mul_f32 v[138:139], v[138:139], v[234:235]
	v_pk_mul_f32 v[140:141], v[140:141], v[236:237]
	v_pk_mul_f32 v[142:143], v[142:143], v[238:239]
	v_cvt_pk_bf16_f32 v166, v136, v137
	v_cvt_pk_bf16_f32 v167, v138, v139
	v_cvt_pk_bf16_f32 v168, v140, v141
	v_cvt_pk_bf16_f32 v169, v142, v143
	global_store_dwordx4 v165, v[166:169], s[12:13] offset:256
	v_add_u32_e32 v165, 0x8000, v165
	ds_write_b128 v160, v[76:79]
	ds_write_b128 v161, v[72:75]
	ds_write_b128 v160, v[12:15] offset:128
	ds_write_b128 v161, v[8:11] offset:128
	s_waitcnt lgkmcnt(0)
	ds_read_b128 v[128:131], v162
	ds_read_b128 v[132:135], v163
	ds_read_b128 v[136:139], v162 offset:128
	ds_read_b128 v[140:143], v163 offset:128
	s_waitcnt vmcnt(8)
	s_waitcnt lgkmcnt(0)
	v_pk_add_f32 v[128:129], v[128:129], v[184:185]
	v_pk_add_f32 v[130:131], v[130:131], v[186:187]
	v_pk_add_f32 v[132:133], v[132:133], v[188:189]
	v_pk_add_f32 v[134:135], v[134:135], v[190:191]
	v_pk_mul_f32 v[128:129], v[128:129], v[176:177]
	v_pk_mul_f32 v[130:131], v[130:131], v[176:177]
	v_pk_mul_f32 v[132:133], v[132:133], v[176:177]
	v_pk_mul_f32 v[134:135], v[134:135], v[176:177]
	v_exp_f32_e32 v128, v128
	v_exp_f32_e32 v129, v129
	v_exp_f32_e32 v130, v130
	v_exp_f32_e32 v131, v131
	v_exp_f32_e32 v132, v132
	v_exp_f32_e32 v133, v133
	v_exp_f32_e32 v134, v134
	v_exp_f32_e32 v135, v135
	v_lshlrev_b32_e32 v232, 16, v216
	v_and_b32_e32 v233, 0xffff0000, v216
	v_lshlrev_b32_e32 v234, 16, v217
	v_and_b32_e32 v235, 0xffff0000, v217
	v_lshlrev_b32_e32 v236, 16, v218
	v_and_b32_e32 v237, 0xffff0000, v218
	v_lshlrev_b32_e32 v238, 16, v219
	v_and_b32_e32 v239, 0xffff0000, v219
	v_pk_add_f32 v[128:129], v[128:129], v[170:171]
	v_pk_add_f32 v[130:131], v[130:131], v[170:171]
	v_pk_add_f32 v[132:133], v[132:133], v[170:171]
	v_pk_add_f32 v[134:135], v[134:135], v[170:171]
	v_rcp_f32_e32 v128, v128
	v_rcp_f32_e32 v129, v129
	v_rcp_f32_e32 v130, v130
	v_rcp_f32_e32 v131, v131
	v_rcp_f32_e32 v132, v132
	v_rcp_f32_e32 v133, v133
	v_rcp_f32_e32 v134, v134
	v_rcp_f32_e32 v135, v135
	s_nop 0
	v_pk_mul_f32 v[128:129], v[128:129], v[232:233]
	v_pk_mul_f32 v[130:131], v[130:131], v[234:235]
	v_pk_mul_f32 v[132:133], v[132:133], v[236:237]
	v_pk_mul_f32 v[134:135], v[134:135], v[238:239]
	v_cvt_pk_bf16_f32 v248, v128, v129
	v_cvt_pk_bf16_f32 v249, v130, v131
	v_cvt_pk_bf16_f32 v250, v132, v133
	v_cvt_pk_bf16_f32 v251, v134, v135
	global_store_dwordx4 v165, v[248:251], s[12:13]
	v_pk_add_f32 v[136:137], v[136:137], v[192:193]
	v_pk_add_f32 v[138:139], v[138:139], v[194:195]
	v_pk_add_f32 v[140:141], v[140:141], v[196:197]
	v_pk_add_f32 v[142:143], v[142:143], v[198:199]
	v_pk_mul_f32 v[136:137], v[136:137], v[176:177]
	v_pk_mul_f32 v[138:139], v[138:139], v[176:177]
	v_pk_mul_f32 v[140:141], v[140:141], v[176:177]
	v_pk_mul_f32 v[142:143], v[142:143], v[176:177]
	v_exp_f32_e32 v136, v136
	v_exp_f32_e32 v137, v137
	v_exp_f32_e32 v138, v138
	v_exp_f32_e32 v139, v139
	v_exp_f32_e32 v140, v140
	v_exp_f32_e32 v141, v141
	v_exp_f32_e32 v142, v142
	v_exp_f32_e32 v143, v143
	v_lshlrev_b32_e32 v232, 16, v220
	v_and_b32_e32 v233, 0xffff0000, v220
	v_lshlrev_b32_e32 v234, 16, v221
	v_and_b32_e32 v235, 0xffff0000, v221
	v_lshlrev_b32_e32 v236, 16, v222
	v_and_b32_e32 v237, 0xffff0000, v222
	v_lshlrev_b32_e32 v238, 16, v223
	v_and_b32_e32 v239, 0xffff0000, v223
	v_pk_add_f32 v[136:137], v[136:137], v[170:171]
	v_pk_add_f32 v[138:139], v[138:139], v[170:171]
	v_pk_add_f32 v[140:141], v[140:141], v[170:171]
	v_pk_add_f32 v[142:143], v[142:143], v[170:171]
	v_rcp_f32_e32 v136, v136
	v_rcp_f32_e32 v137, v137
	v_rcp_f32_e32 v138, v138
	v_rcp_f32_e32 v139, v139
	v_rcp_f32_e32 v140, v140
	v_rcp_f32_e32 v141, v141
	v_rcp_f32_e32 v142, v142
	v_rcp_f32_e32 v143, v143
	s_nop 0
	v_pk_mul_f32 v[136:137], v[136:137], v[232:233]
	v_pk_mul_f32 v[138:139], v[138:139], v[234:235]
	v_pk_mul_f32 v[140:141], v[140:141], v[236:237]
	v_pk_mul_f32 v[142:143], v[142:143], v[238:239]
	v_cvt_pk_bf16_f32 v166, v136, v137
	v_cvt_pk_bf16_f32 v167, v138, v139
	v_cvt_pk_bf16_f32 v168, v140, v141
	v_cvt_pk_bf16_f32 v169, v142, v143
	global_store_dwordx4 v165, v[166:169], s[12:13] offset:256
	v_add_u32_e32 v165, 0x8000, v165
	ds_write_b128 v160, v[68:71]
	ds_write_b128 v161, v[64:67]
	ds_write_b128 v160, v[4:7] offset:128
	ds_write_b128 v161, v[0:3] offset:128
	s_waitcnt lgkmcnt(0)
	ds_read_b128 v[128:131], v162
	ds_read_b128 v[132:135], v163
	ds_read_b128 v[136:139], v162 offset:128
	ds_read_b128 v[140:143], v163 offset:128
	s_waitcnt vmcnt(6)
	s_waitcnt lgkmcnt(0)
	v_pk_add_f32 v[128:129], v[128:129], v[184:185]
	v_pk_add_f32 v[130:131], v[130:131], v[186:187]
	v_pk_add_f32 v[132:133], v[132:133], v[188:189]
	v_pk_add_f32 v[134:135], v[134:135], v[190:191]
	v_pk_mul_f32 v[128:129], v[128:129], v[176:177]
	v_pk_mul_f32 v[130:131], v[130:131], v[176:177]
	v_pk_mul_f32 v[132:133], v[132:133], v[176:177]
	v_pk_mul_f32 v[134:135], v[134:135], v[176:177]
	v_exp_f32_e32 v128, v128
	v_exp_f32_e32 v129, v129
	v_exp_f32_e32 v130, v130
	v_exp_f32_e32 v131, v131
	v_exp_f32_e32 v132, v132
	v_exp_f32_e32 v133, v133
	v_exp_f32_e32 v134, v134
	v_exp_f32_e32 v135, v135
	v_lshlrev_b32_e32 v232, 16, v224
	v_and_b32_e32 v233, 0xffff0000, v224
	v_lshlrev_b32_e32 v234, 16, v225
	v_and_b32_e32 v235, 0xffff0000, v225
	v_lshlrev_b32_e32 v236, 16, v226
	v_and_b32_e32 v237, 0xffff0000, v226
	v_lshlrev_b32_e32 v238, 16, v227
	v_and_b32_e32 v239, 0xffff0000, v227
	v_pk_add_f32 v[128:129], v[128:129], v[170:171]
	v_pk_add_f32 v[130:131], v[130:131], v[170:171]
	v_pk_add_f32 v[132:133], v[132:133], v[170:171]
	v_pk_add_f32 v[134:135], v[134:135], v[170:171]
	v_rcp_f32_e32 v128, v128
	v_rcp_f32_e32 v129, v129
	v_rcp_f32_e32 v130, v130
	v_rcp_f32_e32 v131, v131
	v_rcp_f32_e32 v132, v132
	v_rcp_f32_e32 v133, v133
	v_rcp_f32_e32 v134, v134
	v_rcp_f32_e32 v135, v135
	s_nop 0
	v_pk_mul_f32 v[128:129], v[128:129], v[232:233]
	v_pk_mul_f32 v[130:131], v[130:131], v[234:235]
	v_pk_mul_f32 v[132:133], v[132:133], v[236:237]
	v_pk_mul_f32 v[134:135], v[134:135], v[238:239]
	v_cvt_pk_bf16_f32 v248, v128, v129
	v_cvt_pk_bf16_f32 v249, v130, v131
	v_cvt_pk_bf16_f32 v250, v132, v133
	v_cvt_pk_bf16_f32 v251, v134, v135
	global_store_dwordx4 v165, v[248:251], s[12:13]
	v_pk_add_f32 v[136:137], v[136:137], v[192:193]
	v_pk_add_f32 v[138:139], v[138:139], v[194:195]
	v_pk_add_f32 v[140:141], v[140:141], v[196:197]
	v_pk_add_f32 v[142:143], v[142:143], v[198:199]
	v_pk_mul_f32 v[136:137], v[136:137], v[176:177]
	v_pk_mul_f32 v[138:139], v[138:139], v[176:177]
	v_pk_mul_f32 v[140:141], v[140:141], v[176:177]
	v_pk_mul_f32 v[142:143], v[142:143], v[176:177]
	v_exp_f32_e32 v136, v136
	v_exp_f32_e32 v137, v137
	v_exp_f32_e32 v138, v138
	v_exp_f32_e32 v139, v139
	v_exp_f32_e32 v140, v140
	v_exp_f32_e32 v141, v141
	v_exp_f32_e32 v142, v142
	v_exp_f32_e32 v143, v143
	v_lshlrev_b32_e32 v232, 16, v228
	v_and_b32_e32 v233, 0xffff0000, v228
	v_lshlrev_b32_e32 v234, 16, v229
	v_and_b32_e32 v235, 0xffff0000, v229
	v_lshlrev_b32_e32 v236, 16, v230
	v_and_b32_e32 v237, 0xffff0000, v230
	v_lshlrev_b32_e32 v238, 16, v231
	v_and_b32_e32 v239, 0xffff0000, v231
	v_pk_add_f32 v[136:137], v[136:137], v[170:171]
	v_pk_add_f32 v[138:139], v[138:139], v[170:171]
	v_pk_add_f32 v[140:141], v[140:141], v[170:171]
	v_pk_add_f32 v[142:143], v[142:143], v[170:171]
	v_rcp_f32_e32 v136, v136
	v_rcp_f32_e32 v137, v137
	v_rcp_f32_e32 v138, v138
	v_rcp_f32_e32 v139, v139
	v_rcp_f32_e32 v140, v140
	v_rcp_f32_e32 v141, v141
	v_rcp_f32_e32 v142, v142
	v_rcp_f32_e32 v143, v143
	s_nop 0
	v_pk_mul_f32 v[136:137], v[136:137], v[232:233]
	v_pk_mul_f32 v[138:139], v[138:139], v[234:235]
	v_pk_mul_f32 v[140:141], v[140:141], v[236:237]
	v_pk_mul_f32 v[142:143], v[142:143], v[238:239]
	v_cvt_pk_bf16_f32 v166, v136, v137
	v_cvt_pk_bf16_f32 v167, v138, v139
	v_cvt_pk_bf16_f32 v168, v140, v141
	v_cvt_pk_bf16_f32 v169, v142, v143
	global_store_dwordx4 v165, v[166:169], s[12:13] offset:256
	s_andn2_b64 vcc, exec, s[4:5]
	s_mov_b64 s[0:1], -1
	s_branch .Lqepi_end_5
.Lqepi_5:
	s_bfe_u32 s98, s101, 0x20004
	s_cmp_eq_u32 s98, 0
	s_cbranch_scc1 .Lq5n_done
	s_cmp_eq_u32 s98, 1
	s_cbranch_scc0 .Lq5n_2
	v_mov_b32_e32 v96, v32
	v_mov_b32_e32 v97, v33
	v_mov_b32_e32 v98, v34
	v_mov_b32_e32 v99, v35
	v_mov_b32_e32 v100, v36
	v_mov_b32_e32 v101, v37
	v_mov_b32_e32 v102, v38
	v_mov_b32_e32 v103, v39
	v_mov_b32_e32 v104, v40
	v_mov_b32_e32 v105, v41
	v_mov_b32_e32 v106, v42
	v_mov_b32_e32 v107, v43
	v_mov_b32_e32 v108, v44
	v_mov_b32_e32 v109, v45
	v_mov_b32_e32 v110, v46
	v_mov_b32_e32 v111, v47
	v_mov_b32_e32 v112, v48
	v_mov_b32_e32 v113, v49
	v_mov_b32_e32 v114, v50
	v_mov_b32_e32 v115, v51
	v_mov_b32_e32 v116, v52
	v_mov_b32_e32 v117, v53
	v_mov_b32_e32 v118, v54
	v_mov_b32_e32 v119, v55
	v_mov_b32_e32 v120, v56
	v_mov_b32_e32 v121, v57
	v_mov_b32_e32 v122, v58
	v_mov_b32_e32 v123, v59
	v_mov_b32_e32 v124, v60
	v_mov_b32_e32 v125, v61
	v_mov_b32_e32 v126, v62
	v_mov_b32_e32 v127, v63
	s_branch .Lq5n_done
.Lq5n_2:
	s_cmp_eq_u32 s98, 2
	s_cbranch_scc0 .Lq5n_3
	v_mov_b32_e32 v96, v64
	v_mov_b32_e32 v97, v65
	v_mov_b32_e32 v98, v66
	v_mov_b32_e32 v99, v67
	v_mov_b32_e32 v100, v68
	v_mov_b32_e32 v101, v69
	v_mov_b32_e32 v102, v70
	v_mov_b32_e32 v103, v71
	v_mov_b32_e32 v104, v72
	v_mov_b32_e32 v105, v73
	v_mov_b32_e32 v106, v74
	v_mov_b32_e32 v107, v75
	v_mov_b32_e32 v108, v76
	v_mov_b32_e32 v109, v77
	v_mov_b32_e32 v110, v78
	v_mov_b32_e32 v111, v79
	v_mov_b32_e32 v112, v80
	v_mov_b32_e32 v113, v81
	v_mov_b32_e32 v114, v82
	v_mov_b32_e32 v115, v83
	v_mov_b32_e32 v116, v84
	v_mov_b32_e32 v117, v85
	v_mov_b32_e32 v118, v86
	v_mov_b32_e32 v119, v87
	v_mov_b32_e32 v120, v88
	v_mov_b32_e32 v121, v89
	v_mov_b32_e32 v122, v90
	v_mov_b32_e32 v123, v91
	v_mov_b32_e32 v124, v92
	v_mov_b32_e32 v125, v93
	v_mov_b32_e32 v126, v94
	v_mov_b32_e32 v127, v95
	s_branch .Lq5n_done
.Lq5n_3:
	v_mov_b32_e32 v96, v0
	v_mov_b32_e32 v97, v1
	v_mov_b32_e32 v98, v2
	v_mov_b32_e32 v99, v3
	v_mov_b32_e32 v100, v4
	v_mov_b32_e32 v101, v5
	v_mov_b32_e32 v102, v6
	v_mov_b32_e32 v103, v7
	v_mov_b32_e32 v104, v8
	v_mov_b32_e32 v105, v9
	v_mov_b32_e32 v106, v10
	v_mov_b32_e32 v107, v11
	v_mov_b32_e32 v108, v12
	v_mov_b32_e32 v109, v13
	v_mov_b32_e32 v110, v14
	v_mov_b32_e32 v111, v15
	v_mov_b32_e32 v112, v16
	v_mov_b32_e32 v113, v17
	v_mov_b32_e32 v114, v18
	v_mov_b32_e32 v115, v19
	v_mov_b32_e32 v116, v20
	v_mov_b32_e32 v117, v21
	v_mov_b32_e32 v118, v22
	v_mov_b32_e32 v119, v23
	v_mov_b32_e32 v120, v24
	v_mov_b32_e32 v121, v25
	v_mov_b32_e32 v122, v26
	v_mov_b32_e32 v123, v27
	v_mov_b32_e32 v124, v28
	v_mov_b32_e32 v125, v29
	v_mov_b32_e32 v126, v30
	v_mov_b32_e32 v127, v31
.Lq5n_done:
	v_and_b32_e32 v128, 63, v180
	v_and_b32_e32 v129, 15, v180
	v_bfe_u32 v130, v180, 4, 2
	v_lshrrev_b32_e32 v131, 6, v180
	v_lshlrev_b32_e32 v131, 12, v131
	v_add_u32_e32 v131, 0x20000, v131
	v_and_b32_e32 v132, 7, v129
	v_lshlrev_b32_e32 v133, 1, v130
	v_xor_b32_e32 v132, v133, v132
	v_lshlrev_b32_e32 v132, 4, v132
	v_lshl_add_u32 v132, v129, 8, v132
	v_add_u32_e32 v160, v131, v132
	v_xor_b32_e32 v161, 16, v160
	v_lshrrev_b32_e32 v133, 2, v128
	v_and_b32_e32 v134, 3, v128
	v_and_b32_e32 v135, 7, v133
	v_lshlrev_b32_e32 v136, 1, v134
	v_xor_b32_e32 v136, v136, v135
	v_lshlrev_b32_e32 v136, 4, v136
	v_lshl_add_u32 v136, v133, 8, v136
	v_add_u32_e32 v162, v131, v136
	v_xor_b32_e32 v163, 16, v162
	s_lshr_b32 s99, s98, 1
	s_lshl_b32 s99, s99, 7
	s_lshl_b32 s0, s0, 8
	s_add_i32 s0, s0, s41
	s_add_i32 s0, s0, s99
	v_add_u32_e32 v137, s0, v133
	s_and_b32 s99, s98, 1
	s_lshl_b32 s99, s99, 7
	s_lshl_b32 s1, s1, 8
	s_add_i32 s1, s1, s42
	s_add_i32 s1, s1, s99
	v_lshl_add_u32 v138, v134, 3, s1
	v_lshlrev_b32_e32 v139, 10, v137
	v_lshl_add_u32 v164, v138, 1, v139
	v_lshlrev_b32_e32 v139, 11, v137
	v_lshl_add_u32 v165, v138, 1, v139
	v_lshlrev_b32_e32 v139, 2, v138
	v_mov_b32_e32 v170, 1.0
	v_mov_b32_e32 v171, 1.0
	v_mov_b32_e32 v176, 0xbfb8aa3b
	v_mov_b32_e32 v177, 0xbfb8aa3b
	global_load_dwordx4 v[184:187], v139, s[6:7]
	global_load_dwordx4 v[188:191], v139, s[6:7] offset:16
	s_mov_b64 s[98:99], s[8:9]
	global_load_dwordx4 v[200:203], v164, s[98:99]
	s_add_u32 s98, s98, 0x4000
	s_addc_u32 s99, s99, 0
	global_load_dwordx4 v[204:207], v164, s[98:99]
	s_add_u32 s98, s98, 0x4000
	s_addc_u32 s99, s99, 0
	global_load_dwordx4 v[208:211], v164, s[98:99]
	s_add_u32 s98, s98, 0x4000
	s_addc_u32 s99, s99, 0
	global_load_dwordx4 v[212:215], v164, s[98:99]
	ds_write_b128 v160, v[124:127]
	ds_write_b128 v161, v[120:123]
	s_waitcnt lgkmcnt(0)
	ds_read_b128 v[128:131], v162
	ds_read_b128 v[132:135], v163
	s_waitcnt vmcnt(0)
	s_waitcnt lgkmcnt(0)
	v_pk_add_f32 v[128:129], v[128:129], v[184:185]
	v_pk_add_f32 v[130:131], v[130:131], v[186:187]
	v_pk_add_f32 v[132:133], v[132:133], v[188:189]
	v_pk_add_f32 v[134:135], v[134:135], v[190:191]
	v_pk_mul_f32 v[128:129], v[128:129], v[176:177]
	v_pk_mul_f32 v[130:131], v[130:131], v[176:177]
	v_pk_mul_f32 v[132:133], v[132:133], v[176:177]
	v_pk_mul_f32 v[134:135], v[134:135], v[176:177]
	v_exp_f32_e32 v128, v128
	v_exp_f32_e32 v129, v129
	v_exp_f32_e32 v130, v130
	v_exp_f32_e32 v131, v131
	v_exp_f32_e32 v132, v132
	v_exp_f32_e32 v133, v133
	v_exp_f32_e32 v134, v134
	v_exp_f32_e32 v135, v135
	v_lshlrev_b32_e32 v232, 16, v200
	v_and_b32_e32 v233, 0xffff0000, v200
	v_lshlrev_b32_e32 v234, 16, v201
	v_and_b32_e32 v235, 0xffff0000, v201
	v_lshlrev_b32_e32 v236, 16, v202
	v_and_b32_e32 v237, 0xffff0000, v202
	v_lshlrev_b32_e32 v238, 16, v203
	v_and_b32_e32 v239, 0xffff0000, v203
	v_pk_add_f32 v[128:129], v[128:129], v[170:171]
	v_pk_add_f32 v[130:131], v[130:131], v[170:171]
	v_pk_add_f32 v[132:133], v[132:133], v[170:171]
	v_pk_add_f32 v[134:135], v[134:135], v[170:171]
	v_rcp_f32_e32 v128, v128
	v_rcp_f32_e32 v129, v129
	v_rcp_f32_e32 v130, v130
	v_rcp_f32_e32 v131, v131
	v_rcp_f32_e32 v132, v132
	v_rcp_f32_e32 v133, v133
	v_rcp_f32_e32 v134, v134
	v_rcp_f32_e32 v135, v135
	s_nop 0
	v_pk_mul_f32 v[128:129], v[128:129], v[232:233]
	v_pk_mul_f32 v[130:131], v[130:131], v[234:235]
	v_pk_mul_f32 v[132:133], v[132:133], v[236:237]
	v_pk_mul_f32 v[134:135], v[134:135], v[238:239]
	v_cvt_pk_bf16_f32 v248, v128, v129
	v_cvt_pk_bf16_f32 v249, v130, v131
	v_cvt_pk_bf16_f32 v250, v132, v133
	v_cvt_pk_bf16_f32 v251, v134, v135
	global_store_dwordx4 v165, v[248:251], s[12:13]
	v_add_u32_e32 v165, 0x8000, v165
	ds_write_b128 v160, v[116:119]
	ds_write_b128 v161, v[112:115]
	s_waitcnt lgkmcnt(0)
	ds_read_b128 v[128:131], v162
	ds_read_b128 v[132:135], v163
	s_waitcnt vmcnt(0)
	s_waitcnt lgkmcnt(0)
	v_pk_add_f32 v[128:129], v[128:129], v[184:185]
	v_pk_add_f32 v[130:131], v[130:131], v[186:187]
	v_pk_add_f32 v[132:133], v[132:133], v[188:189]
	v_pk_add_f32 v[134:135], v[134:135], v[190:191]
	v_pk_mul_f32 v[128:129], v[128:129], v[176:177]
	v_pk_mul_f32 v[130:131], v[130:131], v[176:177]
	v_pk_mul_f32 v[132:133], v[132:133], v[176:177]
	v_pk_mul_f32 v[134:135], v[134:135], v[176:177]
	v_exp_f32_e32 v128, v128
	v_exp_f32_e32 v129, v129
	v_exp_f32_e32 v130, v130
	v_exp_f32_e32 v131, v131
	v_exp_f32_e32 v132, v132
	v_exp_f32_e32 v133, v133
	v_exp_f32_e32 v134, v134
	v_exp_f32_e32 v135, v135
	v_lshlrev_b32_e32 v232, 16, v204
	v_and_b32_e32 v233, 0xffff0000, v204
	v_lshlrev_b32_e32 v234, 16, v205
	v_and_b32_e32 v235, 0xffff0000, v205
	v_lshlrev_b32_e32 v236, 16, v206
	v_and_b32_e32 v237, 0xffff0000, v206
	v_lshlrev_b32_e32 v238, 16, v207
	v_and_b32_e32 v239, 0xffff0000, v207
	v_pk_add_f32 v[128:129], v[128:129], v[170:171]
	v_pk_add_f32 v[130:131], v[130:131], v[170:171]
	v_pk_add_f32 v[132:133], v[132:133], v[170:171]
	v_pk_add_f32 v[134:135], v[134:135], v[170:171]
	v_rcp_f32_e32 v128, v128
	v_rcp_f32_e32 v129, v129
	v_rcp_f32_e32 v130, v130
	v_rcp_f32_e32 v131, v131
	v_rcp_f32_e32 v132, v132
	v_rcp_f32_e32 v133, v133
	v_rcp_f32_e32 v134, v134
	v_rcp_f32_e32 v135, v135
	s_nop 0
	v_pk_mul_f32 v[128:129], v[128:129], v[232:233]
	v_pk_mul_f32 v[130:131], v[130:131], v[234:235]
	v_pk_mul_f32 v[132:133], v[132:133], v[236:237]
	v_pk_mul_f32 v[134:135], v[134:135], v[238:239]
	v_cvt_pk_bf16_f32 v248, v128, v129
	v_cvt_pk_bf16_f32 v249, v130, v131
	v_cvt_pk_bf16_f32 v250, v132, v133
	v_cvt_pk_bf16_f32 v251, v134, v135
	global_store_dwordx4 v165, v[248:251], s[12:13]
	v_add_u32_e32 v165, 0x8000, v165
	ds_write_b128 v160, v[108:111]
	ds_write_b128 v161, v[104:107]
	s_waitcnt lgkmcnt(0)
	ds_read_b128 v[128:131], v162
	ds_read_b128 v[132:135], v163
	s_waitcnt vmcnt(0)
	s_waitcnt lgkmcnt(0)
	v_pk_add_f32 v[128:129], v[128:129], v[184:185]
	v_pk_add_f32 v[130:131], v[130:131], v[186:187]
	v_pk_add_f32 v[132:133], v[132:133], v[188:189]
	v_pk_add_f32 v[134:135], v[134:135], v[190:191]
	v_pk_mul_f32 v[128:129], v[128:129], v[176:177]
	v_pk_mul_f32 v[130:131], v[130:131], v[176:177]
	v_pk_mul_f32 v[132:133], v[132:133], v[176:177]
	v_pk_mul_f32 v[134:135], v[134:135], v[176:177]
	v_exp_f32_e32 v128, v128
	v_exp_f32_e32 v129, v129
	v_exp_f32_e32 v130, v130
	v_exp_f32_e32 v131, v131
	v_exp_f32_e32 v132, v132
	v_exp_f32_e32 v133, v133
	v_exp_f32_e32 v134, v134
	v_exp_f32_e32 v135, v135
	v_lshlrev_b32_e32 v232, 16, v208
	v_and_b32_e32 v233, 0xffff0000, v208
	v_lshlrev_b32_e32 v234, 16, v209
	v_and_b32_e32 v235, 0xffff0000, v209
	v_lshlrev_b32_e32 v236, 16, v210
	v_and_b32_e32 v237, 0xffff0000, v210
	v_lshlrev_b32_e32 v238, 16, v211
	v_and_b32_e32 v239, 0xffff0000, v211
	v_pk_add_f32 v[128:129], v[128:129], v[170:171]
	v_pk_add_f32 v[130:131], v[130:131], v[170:171]
	v_pk_add_f32 v[132:133], v[132:133], v[170:171]
	v_pk_add_f32 v[134:135], v[134:135], v[170:171]
	v_rcp_f32_e32 v128, v128
	v_rcp_f32_e32 v129, v129
	v_rcp_f32_e32 v130, v130
	v_rcp_f32_e32 v131, v131
	v_rcp_f32_e32 v132, v132
	v_rcp_f32_e32 v133, v133
	v_rcp_f32_e32 v134, v134
	v_rcp_f32_e32 v135, v135
	s_nop 0
	v_pk_mul_f32 v[128:129], v[128:129], v[232:233]
	v_pk_mul_f32 v[130:131], v[130:131], v[234:235]
	v_pk_mul_f32 v[132:133], v[132:133], v[236:237]
	v_pk_mul_f32 v[134:135], v[134:135], v[238:239]
	v_cvt_pk_bf16_f32 v248, v128, v129
	v_cvt_pk_bf16_f32 v249, v130, v131
	v_cvt_pk_bf16_f32 v250, v132, v133
	v_cvt_pk_bf16_f32 v251, v134, v135
	global_store_dwordx4 v165, v[248:251], s[12:13]
	v_add_u32_e32 v165, 0x8000, v165
	ds_write_b128 v160, v[100:103]
	ds_write_b128 v161, v[96:99]
	s_waitcnt lgkmcnt(0)
	ds_read_b128 v[128:131], v162
	ds_read_b128 v[132:135], v163
	s_waitcnt vmcnt(0)
	s_waitcnt lgkmcnt(0)
	v_pk_add_f32 v[128:129], v[128:129], v[184:185]
	v_pk_add_f32 v[130:131], v[130:131], v[186:187]
	v_pk_add_f32 v[132:133], v[132:133], v[188:189]
	v_pk_add_f32 v[134:135], v[134:135], v[190:191]
	v_pk_mul_f32 v[128:129], v[128:129], v[176:177]
	v_pk_mul_f32 v[130:131], v[130:131], v[176:177]
	v_pk_mul_f32 v[132:133], v[132:133], v[176:177]
	v_pk_mul_f32 v[134:135], v[134:135], v[176:177]
	v_exp_f32_e32 v128, v128
	v_exp_f32_e32 v129, v129
	v_exp_f32_e32 v130, v130
	v_exp_f32_e32 v131, v131
	v_exp_f32_e32 v132, v132
	v_exp_f32_e32 v133, v133
	v_exp_f32_e32 v134, v134
	v_exp_f32_e32 v135, v135
	v_lshlrev_b32_e32 v232, 16, v212
	v_and_b32_e32 v233, 0xffff0000, v212
	v_lshlrev_b32_e32 v234, 16, v213
	v_and_b32_e32 v235, 0xffff0000, v213
	v_lshlrev_b32_e32 v236, 16, v214
	v_and_b32_e32 v237, 0xffff0000, v214
	v_lshlrev_b32_e32 v238, 16, v215
	v_and_b32_e32 v239, 0xffff0000, v215
	v_pk_add_f32 v[128:129], v[128:129], v[170:171]
	v_pk_add_f32 v[130:131], v[130:131], v[170:171]
	v_pk_add_f32 v[132:133], v[132:133], v[170:171]
	v_pk_add_f32 v[134:135], v[134:135], v[170:171]
	v_rcp_f32_e32 v128, v128
	v_rcp_f32_e32 v129, v129
	v_rcp_f32_e32 v130, v130
	v_rcp_f32_e32 v131, v131
	v_rcp_f32_e32 v132, v132
	v_rcp_f32_e32 v133, v133
	v_rcp_f32_e32 v134, v134
	v_rcp_f32_e32 v135, v135
	s_nop 0
	v_pk_mul_f32 v[128:129], v[128:129], v[232:233]
	v_pk_mul_f32 v[130:131], v[130:131], v[234:235]
	v_pk_mul_f32 v[132:133], v[132:133], v[236:237]
	v_pk_mul_f32 v[134:135], v[134:135], v[238:239]
	v_cvt_pk_bf16_f32 v248, v128, v129
	v_cvt_pk_bf16_f32 v249, v130, v131
	v_cvt_pk_bf16_f32 v250, v132, v133
	v_cvt_pk_bf16_f32 v251, v134, v135
	global_store_dwordx4 v165, v[248:251], s[12:13]
	s_andn2_b64 vcc, exec, s[4:5]
	s_mov_b64 s[0:1], -1
.Lqepi_end_5:
	s_cbranch_vccnz .LBB0_1396
	s_andn2_b64 vcc, exec, s[10:11]
	s_cbranch_vccnz .LBB0_1395
	s_barrier
	s_branch .LBB0_1395
